# scan2 main loop software-pipelined (14-row prefetch ring, counted vmcnt) on top of batched stats_rows
# baseline (speedup 1.0000x reference)
.LBB0_550:
	s_lshl_b32 s0, s3, 1
	s_and_b32 s0, s0, 0xffffffbe
	v_or_b32_e32 v8, s0, v18
	v_ashrrev_i32_e32 v9, 31, v8
	v_lshlrev_b64 v[8:9], 15, v[8:9]
	s_lshl_b32 s0, s3, 9
	v_lshl_add_u64 v[8:9], v[2:3], 0, v[8:9]
	s_and_b32 s54, s0, 0x4000
	v_lshl_add_u64 v[8:9], v[8:9], 0, s[54:55]
	s_mov_b32 s0, -16
	v_mov_b64_e32 v[10:11], v[0:1]
	v_lshl_add_u64 v[12:13], s[70:71], 0, v[10:11]
	v_add_co_u32_e32 v14, vcc, 0x2e895000, v12
	s_nop 1
	v_addc_co_u32_e32 v15, vcc, 0, v13, vcc
	v_add_co_u32_e32 v20, vcc, 0x16485000, v12
	s_nop 1
	v_addc_co_u32_e32 v21, vcc, 0, v13, vcc
	v_add_co_u32_e32 v12, vcc, 0x2a895000, v12
	s_nop 1
	v_addc_co_u32_e32 v13, vcc, 0, v13, vcc
	v_lshl_add_u64 v[22:23], s[70:71], 0, v[8:9]
	v_add_co_u32_e32 v22, vcc, 0xc00, v22
	s_nop 1
	v_addc_co_u32_e32 v23, vcc, 0, v23, vcc
	global_load_dword v88, v[12:13], off offset:-4096 nt
	global_load_dword v89, v[14:15], off offset:-4096 nt
	global_load_dword v90, v[20:21], off offset:-4096 nt
	global_load_dword v91, v[12:13], off offset:-3840 nt
	global_load_dword v92, v[14:15], off offset:-3840 nt
	global_load_dword v93, v[20:21], off offset:-3840 nt
	global_load_dword v94, v[12:13], off offset:-3584 nt
	global_load_dword v95, v[14:15], off offset:-3584 nt
	global_load_dword v96, v[20:21], off offset:-3584 nt
	global_load_dword v97, v[12:13], off offset:-3328 nt
	global_load_dword v98, v[14:15], off offset:-3328 nt
	global_load_dword v99, v[20:21], off offset:-3328 nt
	global_load_dword v100, v[12:13], off offset:-3072 nt
	global_load_dword v101, v[14:15], off offset:-3072 nt
	global_load_dword v102, v[20:21], off offset:-3072 nt
	global_load_dword v103, v[12:13], off offset:-2816 nt
	global_load_dword v104, v[14:15], off offset:-2816 nt
	global_load_dword v105, v[20:21], off offset:-2816 nt
	global_load_dword v106, v[12:13], off offset:-2560 nt
	global_load_dword v107, v[14:15], off offset:-2560 nt
	global_load_dword v108, v[20:21], off offset:-2560 nt
	global_load_dword v109, v[12:13], off offset:-2304 nt
	global_load_dword v110, v[14:15], off offset:-2304 nt
	global_load_dword v111, v[20:21], off offset:-2304 nt
	global_load_dword v112, v[12:13], off offset:-2048 nt
	global_load_dword v113, v[14:15], off offset:-2048 nt
	global_load_dword v114, v[20:21], off offset:-2048 nt
	global_load_dword v115, v[12:13], off offset:-1792 nt
	global_load_dword v116, v[14:15], off offset:-1792 nt
	global_load_dword v117, v[20:21], off offset:-1792 nt
	global_load_dword v118, v[12:13], off offset:-1536 nt
	global_load_dword v119, v[14:15], off offset:-1536 nt
	global_load_dword v120, v[20:21], off offset:-1536 nt
	global_load_dword v121, v[12:13], off offset:-1280 nt
	global_load_dword v122, v[14:15], off offset:-1280 nt
	global_load_dword v123, v[20:21], off offset:-1280 nt
	global_load_dword v124, v[12:13], off offset:-1024 nt
	global_load_dword v125, v[14:15], off offset:-1024 nt
	global_load_dword v126, v[20:21], off offset:-1024 nt
	global_load_dword v127, v[12:13], off offset:-768 nt
	global_load_dword v128, v[14:15], off offset:-768 nt
	global_load_dword v129, v[20:21], off offset:-768 nt
	s_waitcnt vmcnt(39)
	v_lshlrev_b32_e32 v24, 16, v88
	v_and_b32_e32 v25, 0xffff0000, v88
	v_lshlrev_b32_e32 v28, 16, v90
	v_and_b32_e32 v29, 0xffff0000, v90
	v_pk_mul_f32 v[24:25], v[24:25], s[56:57] op_sel_hi:[1,0]
	v_pk_mul_f32 v[30:31], v[28:29], s[58:59] op_sel_hi:[1,0]
	v_lshlrev_b32_e32 v26, 16, v89
	v_and_b32_e32 v27, 0xffff0000, v89
	v_exp_f32_e32 v24, v24
	v_exp_f32_e32 v25, v25
	v_exp_f32_e32 v30, v30
	v_exp_f32_e32 v31, v31
	global_load_dword v130, v[12:13], off offset:-512 nt
	global_load_dword v131, v[14:15], off offset:-512 nt
	global_load_dword v132, v[20:21], off offset:-512 nt
	s_waitcnt vmcnt(39)
	v_lshlrev_b32_e32 v38, 16, v91
	v_and_b32_e32 v39, 0xffff0000, v91
	v_lshlrev_b32_e32 v42, 16, v93
	v_and_b32_e32 v43, 0xffff0000, v93
	v_pk_mul_f32 v[38:39], v[38:39], s[56:57] op_sel_hi:[1,0]
	v_pk_mul_f32 v[44:45], v[42:43], s[58:59] op_sel_hi:[1,0]
	v_lshlrev_b32_e32 v40, 16, v92
	v_and_b32_e32 v41, 0xffff0000, v92
	v_exp_f32_e32 v38, v38
	v_exp_f32_e32 v39, v39
	v_exp_f32_e32 v44, v44
	v_exp_f32_e32 v45, v45
	v_pk_add_f32 v[30:31], v[30:31], 1.0 op_sel_hi:[1,0]
	v_rcp_f32_e32 v30, v30
	v_rcp_f32_e32 v31, v31
	v_pk_fma_f32 v[6:7], v[6:7], v[24:25], v[26:27]
	v_pk_mul_f32 v[32:33], v[6:7], v[28:29]
	v_pk_mul_f32 v[32:33], v[32:33], v[30:31]
	v_cvt_pk_bf16_f32 v34, v32, v33
	global_store_dword v[22:23], v34, off offset:-4096
	global_load_dword v133, v[12:13], off offset:-256 nt
	global_load_dword v134, v[14:15], off offset:-256 nt
	global_load_dword v135, v[20:21], off offset:-256 nt
	s_waitcnt vmcnt(40)
	v_lshlrev_b32_e32 v52, 16, v94
	v_and_b32_e32 v53, 0xffff0000, v94
	v_lshlrev_b32_e32 v56, 16, v96
	v_and_b32_e32 v57, 0xffff0000, v96
	v_pk_mul_f32 v[52:53], v[52:53], s[56:57] op_sel_hi:[1,0]
	v_pk_mul_f32 v[58:59], v[56:57], s[58:59] op_sel_hi:[1,0]
	v_lshlrev_b32_e32 v54, 16, v95
	v_and_b32_e32 v55, 0xffff0000, v95
	v_exp_f32_e32 v52, v52
	v_exp_f32_e32 v53, v53
	v_exp_f32_e32 v58, v58
	v_exp_f32_e32 v59, v59
	v_pk_add_f32 v[44:45], v[44:45], 1.0 op_sel_hi:[1,0]
	v_rcp_f32_e32 v44, v44
	v_rcp_f32_e32 v45, v45
	v_pk_fma_f32 v[6:7], v[6:7], v[38:39], v[40:41]
	v_pk_mul_f32 v[46:47], v[6:7], v[42:43]
	v_pk_mul_f32 v[46:47], v[46:47], v[44:45]
	v_cvt_pk_bf16_f32 v48, v46, v47
	global_store_dword v[22:23], v48, off offset:-3968
	global_load_dword v88, v[12:13], off nt
	global_load_dword v89, v[14:15], off nt
	global_load_dword v90, v[20:21], off nt
	s_waitcnt vmcnt(41)
	v_lshlrev_b32_e32 v24, 16, v97
	v_and_b32_e32 v25, 0xffff0000, v97
	v_lshlrev_b32_e32 v28, 16, v99
	v_and_b32_e32 v29, 0xffff0000, v99
	v_pk_mul_f32 v[24:25], v[24:25], s[56:57] op_sel_hi:[1,0]
	v_pk_mul_f32 v[30:31], v[28:29], s[58:59] op_sel_hi:[1,0]
	v_lshlrev_b32_e32 v26, 16, v98
	v_and_b32_e32 v27, 0xffff0000, v98
	v_exp_f32_e32 v24, v24
	v_exp_f32_e32 v25, v25
	v_exp_f32_e32 v30, v30
	v_exp_f32_e32 v31, v31
	v_pk_add_f32 v[58:59], v[58:59], 1.0 op_sel_hi:[1,0]
	v_rcp_f32_e32 v58, v58
	v_rcp_f32_e32 v59, v59
	v_pk_fma_f32 v[6:7], v[6:7], v[52:53], v[54:55]
	v_pk_mul_f32 v[60:61], v[6:7], v[56:57]
	v_pk_mul_f32 v[60:61], v[60:61], v[58:59]
	v_cvt_pk_bf16_f32 v62, v60, v61
	global_store_dword v[22:23], v62, off offset:-3840
	global_load_dword v91, v[12:13], off offset:256 nt
	global_load_dword v92, v[14:15], off offset:256 nt
	global_load_dword v93, v[20:21], off offset:256 nt
	s_waitcnt vmcnt(42)
	v_lshlrev_b32_e32 v38, 16, v100
	v_and_b32_e32 v39, 0xffff0000, v100
	v_lshlrev_b32_e32 v42, 16, v102
	v_and_b32_e32 v43, 0xffff0000, v102
	v_pk_mul_f32 v[38:39], v[38:39], s[56:57] op_sel_hi:[1,0]
	v_pk_mul_f32 v[44:45], v[42:43], s[58:59] op_sel_hi:[1,0]
	v_lshlrev_b32_e32 v40, 16, v101
	v_and_b32_e32 v41, 0xffff0000, v101
	v_exp_f32_e32 v38, v38
	v_exp_f32_e32 v39, v39
	v_exp_f32_e32 v44, v44
	v_exp_f32_e32 v45, v45
	v_pk_add_f32 v[30:31], v[30:31], 1.0 op_sel_hi:[1,0]
	v_rcp_f32_e32 v30, v30
	v_rcp_f32_e32 v31, v31
	v_pk_fma_f32 v[6:7], v[6:7], v[24:25], v[26:27]
	v_pk_mul_f32 v[32:33], v[6:7], v[28:29]
	v_pk_mul_f32 v[32:33], v[32:33], v[30:31]
	v_cvt_pk_bf16_f32 v34, v32, v33
	global_store_dword v[22:23], v34, off offset:-3712
	global_load_dword v94, v[12:13], off offset:512 nt
	global_load_dword v95, v[14:15], off offset:512 nt
	global_load_dword v96, v[20:21], off offset:512 nt
	s_waitcnt vmcnt(43)
	v_lshlrev_b32_e32 v52, 16, v103
	v_and_b32_e32 v53, 0xffff0000, v103
	v_lshlrev_b32_e32 v56, 16, v105
	v_and_b32_e32 v57, 0xffff0000, v105
	v_pk_mul_f32 v[52:53], v[52:53], s[56:57] op_sel_hi:[1,0]
	v_pk_mul_f32 v[58:59], v[56:57], s[58:59] op_sel_hi:[1,0]
	v_lshlrev_b32_e32 v54, 16, v104
	v_and_b32_e32 v55, 0xffff0000, v104
	v_exp_f32_e32 v52, v52
	v_exp_f32_e32 v53, v53
	v_exp_f32_e32 v58, v58
	v_exp_f32_e32 v59, v59
	v_pk_add_f32 v[44:45], v[44:45], 1.0 op_sel_hi:[1,0]
	v_rcp_f32_e32 v44, v44
	v_rcp_f32_e32 v45, v45
	v_pk_fma_f32 v[6:7], v[6:7], v[38:39], v[40:41]
	v_pk_mul_f32 v[46:47], v[6:7], v[42:43]
	v_pk_mul_f32 v[46:47], v[46:47], v[44:45]
	v_cvt_pk_bf16_f32 v48, v46, v47
	global_store_dword v[22:23], v48, off offset:-3584
	global_load_dword v97, v[12:13], off offset:768 nt
	global_load_dword v98, v[14:15], off offset:768 nt
	global_load_dword v99, v[20:21], off offset:768 nt
	s_waitcnt vmcnt(44)
	v_lshlrev_b32_e32 v24, 16, v106
	v_and_b32_e32 v25, 0xffff0000, v106
	v_lshlrev_b32_e32 v28, 16, v108
	v_and_b32_e32 v29, 0xffff0000, v108
	v_pk_mul_f32 v[24:25], v[24:25], s[56:57] op_sel_hi:[1,0]
	v_pk_mul_f32 v[30:31], v[28:29], s[58:59] op_sel_hi:[1,0]
	v_lshlrev_b32_e32 v26, 16, v107
	v_and_b32_e32 v27, 0xffff0000, v107
	v_exp_f32_e32 v24, v24
	v_exp_f32_e32 v25, v25
	v_exp_f32_e32 v30, v30
	v_exp_f32_e32 v31, v31
	v_pk_add_f32 v[58:59], v[58:59], 1.0 op_sel_hi:[1,0]
	v_rcp_f32_e32 v58, v58
	v_rcp_f32_e32 v59, v59
	v_pk_fma_f32 v[6:7], v[6:7], v[52:53], v[54:55]
	v_pk_mul_f32 v[60:61], v[6:7], v[56:57]
	v_pk_mul_f32 v[60:61], v[60:61], v[58:59]
	v_cvt_pk_bf16_f32 v62, v60, v61
	global_store_dword v[22:23], v62, off offset:-3456
	global_load_dword v100, v[12:13], off offset:1024 nt
	global_load_dword v101, v[14:15], off offset:1024 nt
	global_load_dword v102, v[20:21], off offset:1024 nt
	s_waitcnt vmcnt(45)
	v_lshlrev_b32_e32 v38, 16, v109
	v_and_b32_e32 v39, 0xffff0000, v109
	v_lshlrev_b32_e32 v42, 16, v111
	v_and_b32_e32 v43, 0xffff0000, v111
	v_pk_mul_f32 v[38:39], v[38:39], s[56:57] op_sel_hi:[1,0]
	v_pk_mul_f32 v[44:45], v[42:43], s[58:59] op_sel_hi:[1,0]
	v_lshlrev_b32_e32 v40, 16, v110
	v_and_b32_e32 v41, 0xffff0000, v110
	v_exp_f32_e32 v38, v38
	v_exp_f32_e32 v39, v39
	v_exp_f32_e32 v44, v44
	v_exp_f32_e32 v45, v45
	v_pk_add_f32 v[30:31], v[30:31], 1.0 op_sel_hi:[1,0]
	v_rcp_f32_e32 v30, v30
	v_rcp_f32_e32 v31, v31
	v_pk_fma_f32 v[6:7], v[6:7], v[24:25], v[26:27]
	v_pk_mul_f32 v[32:33], v[6:7], v[28:29]
	v_pk_mul_f32 v[32:33], v[32:33], v[30:31]
	v_cvt_pk_bf16_f32 v34, v32, v33
	global_store_dword v[22:23], v34, off offset:-3328
	global_load_dword v103, v[12:13], off offset:1280 nt
	global_load_dword v104, v[14:15], off offset:1280 nt
	global_load_dword v105, v[20:21], off offset:1280 nt
	s_waitcnt vmcnt(46)
	v_lshlrev_b32_e32 v52, 16, v112
	v_and_b32_e32 v53, 0xffff0000, v112
	v_lshlrev_b32_e32 v56, 16, v114
	v_and_b32_e32 v57, 0xffff0000, v114
	v_pk_mul_f32 v[52:53], v[52:53], s[56:57] op_sel_hi:[1,0]
	v_pk_mul_f32 v[58:59], v[56:57], s[58:59] op_sel_hi:[1,0]
	v_lshlrev_b32_e32 v54, 16, v113
	v_and_b32_e32 v55, 0xffff0000, v113
	v_exp_f32_e32 v52, v52
	v_exp_f32_e32 v53, v53
	v_exp_f32_e32 v58, v58
	v_exp_f32_e32 v59, v59
	v_pk_add_f32 v[44:45], v[44:45], 1.0 op_sel_hi:[1,0]
	v_rcp_f32_e32 v44, v44
	v_rcp_f32_e32 v45, v45
	v_pk_fma_f32 v[6:7], v[6:7], v[38:39], v[40:41]
	v_pk_mul_f32 v[46:47], v[6:7], v[42:43]
	v_pk_mul_f32 v[46:47], v[46:47], v[44:45]
	v_cvt_pk_bf16_f32 v48, v46, v47
	global_store_dword v[22:23], v48, off offset:-3200
	global_load_dword v106, v[12:13], off offset:1536 nt
	global_load_dword v107, v[14:15], off offset:1536 nt
	global_load_dword v108, v[20:21], off offset:1536 nt
	s_waitcnt vmcnt(47)
	v_lshlrev_b32_e32 v24, 16, v115
	v_and_b32_e32 v25, 0xffff0000, v115
	v_lshlrev_b32_e32 v28, 16, v117
	v_and_b32_e32 v29, 0xffff0000, v117
	v_pk_mul_f32 v[24:25], v[24:25], s[56:57] op_sel_hi:[1,0]
	v_pk_mul_f32 v[30:31], v[28:29], s[58:59] op_sel_hi:[1,0]
	v_lshlrev_b32_e32 v26, 16, v116
	v_and_b32_e32 v27, 0xffff0000, v116
	v_exp_f32_e32 v24, v24
	v_exp_f32_e32 v25, v25
	v_exp_f32_e32 v30, v30
	v_exp_f32_e32 v31, v31
	v_pk_add_f32 v[58:59], v[58:59], 1.0 op_sel_hi:[1,0]
	v_rcp_f32_e32 v58, v58
	v_rcp_f32_e32 v59, v59
	v_pk_fma_f32 v[6:7], v[6:7], v[52:53], v[54:55]
	v_pk_mul_f32 v[60:61], v[6:7], v[56:57]
	v_pk_mul_f32 v[60:61], v[60:61], v[58:59]
	v_cvt_pk_bf16_f32 v62, v60, v61
	global_store_dword v[22:23], v62, off offset:-3072
	global_load_dword v109, v[12:13], off offset:1792 nt
	global_load_dword v110, v[14:15], off offset:1792 nt
	global_load_dword v111, v[20:21], off offset:1792 nt
	s_waitcnt vmcnt(48)
	v_lshlrev_b32_e32 v38, 16, v118
	v_and_b32_e32 v39, 0xffff0000, v118
	v_lshlrev_b32_e32 v42, 16, v120
	v_and_b32_e32 v43, 0xffff0000, v120
	v_pk_mul_f32 v[38:39], v[38:39], s[56:57] op_sel_hi:[1,0]
	v_pk_mul_f32 v[44:45], v[42:43], s[58:59] op_sel_hi:[1,0]
	v_lshlrev_b32_e32 v40, 16, v119
	v_and_b32_e32 v41, 0xffff0000, v119
	v_exp_f32_e32 v38, v38
	v_exp_f32_e32 v39, v39
	v_exp_f32_e32 v44, v44
	v_exp_f32_e32 v45, v45
	v_pk_add_f32 v[30:31], v[30:31], 1.0 op_sel_hi:[1,0]
	v_rcp_f32_e32 v30, v30
	v_rcp_f32_e32 v31, v31
	v_pk_fma_f32 v[6:7], v[6:7], v[24:25], v[26:27]
	v_pk_mul_f32 v[32:33], v[6:7], v[28:29]
	v_pk_mul_f32 v[32:33], v[32:33], v[30:31]
	v_cvt_pk_bf16_f32 v34, v32, v33
	global_store_dword v[22:23], v34, off offset:-2944
	global_load_dword v112, v[12:13], off offset:2048 nt
	global_load_dword v113, v[14:15], off offset:2048 nt
	global_load_dword v114, v[20:21], off offset:2048 nt
	s_waitcnt vmcnt(49)
	v_lshlrev_b32_e32 v52, 16, v121
	v_and_b32_e32 v53, 0xffff0000, v121
	v_lshlrev_b32_e32 v56, 16, v123
	v_and_b32_e32 v57, 0xffff0000, v123
	v_pk_mul_f32 v[52:53], v[52:53], s[56:57] op_sel_hi:[1,0]
	v_pk_mul_f32 v[58:59], v[56:57], s[58:59] op_sel_hi:[1,0]
	v_lshlrev_b32_e32 v54, 16, v122
	v_and_b32_e32 v55, 0xffff0000, v122
	v_exp_f32_e32 v52, v52
	v_exp_f32_e32 v53, v53
	v_exp_f32_e32 v58, v58
	v_exp_f32_e32 v59, v59
	v_pk_add_f32 v[44:45], v[44:45], 1.0 op_sel_hi:[1,0]
	v_rcp_f32_e32 v44, v44
	v_rcp_f32_e32 v45, v45
	v_pk_fma_f32 v[6:7], v[6:7], v[38:39], v[40:41]
	v_pk_mul_f32 v[46:47], v[6:7], v[42:43]
	v_pk_mul_f32 v[46:47], v[46:47], v[44:45]
	v_cvt_pk_bf16_f32 v48, v46, v47
	global_store_dword v[22:23], v48, off offset:-2816
	global_load_dword v115, v[12:13], off offset:2304 nt
	global_load_dword v116, v[14:15], off offset:2304 nt
	global_load_dword v117, v[20:21], off offset:2304 nt
	s_waitcnt vmcnt(50)
	v_lshlrev_b32_e32 v24, 16, v124
	v_and_b32_e32 v25, 0xffff0000, v124
	v_lshlrev_b32_e32 v28, 16, v126
	v_and_b32_e32 v29, 0xffff0000, v126
	v_pk_mul_f32 v[24:25], v[24:25], s[56:57] op_sel_hi:[1,0]
	v_pk_mul_f32 v[30:31], v[28:29], s[58:59] op_sel_hi:[1,0]
	v_lshlrev_b32_e32 v26, 16, v125
	v_and_b32_e32 v27, 0xffff0000, v125
	v_exp_f32_e32 v24, v24
	v_exp_f32_e32 v25, v25
	v_exp_f32_e32 v30, v30
	v_exp_f32_e32 v31, v31
	v_pk_add_f32 v[58:59], v[58:59], 1.0 op_sel_hi:[1,0]
	v_rcp_f32_e32 v58, v58
	v_rcp_f32_e32 v59, v59
	v_pk_fma_f32 v[6:7], v[6:7], v[52:53], v[54:55]
	v_pk_mul_f32 v[60:61], v[6:7], v[56:57]
	v_pk_mul_f32 v[60:61], v[60:61], v[58:59]
	v_cvt_pk_bf16_f32 v62, v60, v61
	global_store_dword v[22:23], v62, off offset:-2688
	global_load_dword v118, v[12:13], off offset:2560 nt
	global_load_dword v119, v[14:15], off offset:2560 nt
	global_load_dword v120, v[20:21], off offset:2560 nt
	s_waitcnt vmcnt(51)
	v_lshlrev_b32_e32 v38, 16, v127
	v_and_b32_e32 v39, 0xffff0000, v127
	v_lshlrev_b32_e32 v42, 16, v129
	v_and_b32_e32 v43, 0xffff0000, v129
	v_pk_mul_f32 v[38:39], v[38:39], s[56:57] op_sel_hi:[1,0]
	v_pk_mul_f32 v[44:45], v[42:43], s[58:59] op_sel_hi:[1,0]
	v_lshlrev_b32_e32 v40, 16, v128
	v_and_b32_e32 v41, 0xffff0000, v128
	v_exp_f32_e32 v38, v38
	v_exp_f32_e32 v39, v39
	v_exp_f32_e32 v44, v44
	v_exp_f32_e32 v45, v45
	v_pk_add_f32 v[30:31], v[30:31], 1.0 op_sel_hi:[1,0]
	v_rcp_f32_e32 v30, v30
	v_rcp_f32_e32 v31, v31
	v_pk_fma_f32 v[6:7], v[6:7], v[24:25], v[26:27]
	v_pk_mul_f32 v[32:33], v[6:7], v[28:29]
	v_pk_mul_f32 v[32:33], v[32:33], v[30:31]
	v_cvt_pk_bf16_f32 v34, v32, v33
	global_store_dword v[22:23], v34, off offset:-2560
	global_load_dword v121, v[12:13], off offset:2816 nt
	global_load_dword v122, v[14:15], off offset:2816 nt
	global_load_dword v123, v[20:21], off offset:2816 nt
	s_waitcnt vmcnt(52)
	v_lshlrev_b32_e32 v52, 16, v130
	v_and_b32_e32 v53, 0xffff0000, v130
	v_lshlrev_b32_e32 v56, 16, v132
	v_and_b32_e32 v57, 0xffff0000, v132
	v_pk_mul_f32 v[52:53], v[52:53], s[56:57] op_sel_hi:[1,0]
	v_pk_mul_f32 v[58:59], v[56:57], s[58:59] op_sel_hi:[1,0]
	v_lshlrev_b32_e32 v54, 16, v131
	v_and_b32_e32 v55, 0xffff0000, v131
	v_exp_f32_e32 v52, v52
	v_exp_f32_e32 v53, v53
	v_exp_f32_e32 v58, v58
	v_exp_f32_e32 v59, v59
	v_pk_add_f32 v[44:45], v[44:45], 1.0 op_sel_hi:[1,0]
	v_rcp_f32_e32 v44, v44
	v_rcp_f32_e32 v45, v45
	v_pk_fma_f32 v[6:7], v[6:7], v[38:39], v[40:41]
	v_pk_mul_f32 v[46:47], v[6:7], v[42:43]
	v_pk_mul_f32 v[46:47], v[46:47], v[44:45]
	v_cvt_pk_bf16_f32 v48, v46, v47
	global_store_dword v[22:23], v48, off offset:-2432
	global_load_dword v124, v[12:13], off offset:3072 nt
	global_load_dword v125, v[14:15], off offset:3072 nt
	global_load_dword v126, v[20:21], off offset:3072 nt
	s_waitcnt vmcnt(52)
	v_lshlrev_b32_e32 v24, 16, v133
	v_and_b32_e32 v25, 0xffff0000, v133
	v_lshlrev_b32_e32 v28, 16, v135
	v_and_b32_e32 v29, 0xffff0000, v135
	v_pk_mul_f32 v[24:25], v[24:25], s[56:57] op_sel_hi:[1,0]
	v_pk_mul_f32 v[30:31], v[28:29], s[58:59] op_sel_hi:[1,0]
	v_lshlrev_b32_e32 v26, 16, v134
	v_and_b32_e32 v27, 0xffff0000, v134
	v_exp_f32_e32 v24, v24
	v_exp_f32_e32 v25, v25
	v_exp_f32_e32 v30, v30
	v_exp_f32_e32 v31, v31
	v_pk_add_f32 v[58:59], v[58:59], 1.0 op_sel_hi:[1,0]
	v_rcp_f32_e32 v58, v58
	v_rcp_f32_e32 v59, v59
	v_pk_fma_f32 v[6:7], v[6:7], v[52:53], v[54:55]
	v_pk_mul_f32 v[60:61], v[6:7], v[56:57]
	v_pk_mul_f32 v[60:61], v[60:61], v[58:59]
	v_cvt_pk_bf16_f32 v62, v60, v61
	global_store_dword v[22:23], v62, off offset:-2304
	global_load_dword v127, v[12:13], off offset:3328 nt
	global_load_dword v128, v[14:15], off offset:3328 nt
	global_load_dword v129, v[20:21], off offset:3328 nt
	s_waitcnt vmcnt(52)
	v_lshlrev_b32_e32 v38, 16, v88
	v_and_b32_e32 v39, 0xffff0000, v88
	v_lshlrev_b32_e32 v42, 16, v90
	v_and_b32_e32 v43, 0xffff0000, v90
	v_pk_mul_f32 v[38:39], v[38:39], s[56:57] op_sel_hi:[1,0]
	v_pk_mul_f32 v[44:45], v[42:43], s[58:59] op_sel_hi:[1,0]
	v_lshlrev_b32_e32 v40, 16, v89
	v_and_b32_e32 v41, 0xffff0000, v89
	v_exp_f32_e32 v38, v38
	v_exp_f32_e32 v39, v39
	v_exp_f32_e32 v44, v44
	v_exp_f32_e32 v45, v45
	v_pk_add_f32 v[30:31], v[30:31], 1.0 op_sel_hi:[1,0]
	v_rcp_f32_e32 v30, v30
	v_rcp_f32_e32 v31, v31
	v_pk_fma_f32 v[6:7], v[6:7], v[24:25], v[26:27]
	v_pk_mul_f32 v[32:33], v[6:7], v[28:29]
	v_pk_mul_f32 v[32:33], v[32:33], v[30:31]
	v_cvt_pk_bf16_f32 v34, v32, v33
	global_store_dword v[22:23], v34, off offset:-2176
	global_load_dword v130, v[12:13], off offset:3584 nt
	global_load_dword v131, v[14:15], off offset:3584 nt
	global_load_dword v132, v[20:21], off offset:3584 nt
	s_waitcnt vmcnt(52)
	v_lshlrev_b32_e32 v52, 16, v91
	v_and_b32_e32 v53, 0xffff0000, v91
	v_lshlrev_b32_e32 v56, 16, v93
	v_and_b32_e32 v57, 0xffff0000, v93
	v_pk_mul_f32 v[52:53], v[52:53], s[56:57] op_sel_hi:[1,0]
	v_pk_mul_f32 v[58:59], v[56:57], s[58:59] op_sel_hi:[1,0]
	v_lshlrev_b32_e32 v54, 16, v92
	v_and_b32_e32 v55, 0xffff0000, v92
	v_exp_f32_e32 v52, v52
	v_exp_f32_e32 v53, v53
	v_exp_f32_e32 v58, v58
	v_exp_f32_e32 v59, v59
	v_pk_add_f32 v[44:45], v[44:45], 1.0 op_sel_hi:[1,0]
	v_rcp_f32_e32 v44, v44
	v_rcp_f32_e32 v45, v45
	v_pk_fma_f32 v[6:7], v[6:7], v[38:39], v[40:41]
	v_pk_mul_f32 v[46:47], v[6:7], v[42:43]
	v_pk_mul_f32 v[46:47], v[46:47], v[44:45]
	v_cvt_pk_bf16_f32 v48, v46, v47
	global_store_dword v[22:23], v48, off offset:-2048
	global_load_dword v133, v[12:13], off offset:3840 nt
	global_load_dword v134, v[14:15], off offset:3840 nt
	global_load_dword v135, v[20:21], off offset:3840 nt
	s_waitcnt vmcnt(52)
	v_lshlrev_b32_e32 v24, 16, v94
	v_and_b32_e32 v25, 0xffff0000, v94
	v_lshlrev_b32_e32 v28, 16, v96
	v_and_b32_e32 v29, 0xffff0000, v96
	v_pk_mul_f32 v[24:25], v[24:25], s[56:57] op_sel_hi:[1,0]
	v_pk_mul_f32 v[30:31], v[28:29], s[58:59] op_sel_hi:[1,0]
	v_lshlrev_b32_e32 v26, 16, v95
	v_and_b32_e32 v27, 0xffff0000, v95
	v_exp_f32_e32 v24, v24
	v_exp_f32_e32 v25, v25
	v_exp_f32_e32 v30, v30
	v_exp_f32_e32 v31, v31
	v_pk_add_f32 v[58:59], v[58:59], 1.0 op_sel_hi:[1,0]
	v_rcp_f32_e32 v58, v58
	v_rcp_f32_e32 v59, v59
	v_pk_fma_f32 v[6:7], v[6:7], v[52:53], v[54:55]
	v_pk_mul_f32 v[60:61], v[6:7], v[56:57]
	v_pk_mul_f32 v[60:61], v[60:61], v[58:59]
	v_cvt_pk_bf16_f32 v62, v60, v61
	global_store_dword v[22:23], v62, off offset:-1920
	v_lshl_add_u64 v[12:13], v[12:13], 0, s[60:61]
	v_lshl_add_u64 v[12:13], v[12:13], 0, s[60:61]
	v_lshl_add_u64 v[14:15], v[14:15], 0, s[60:61]
	v_lshl_add_u64 v[14:15], v[14:15], 0, s[60:61]
	v_lshl_add_u64 v[20:21], v[20:21], 0, s[60:61]
	v_lshl_add_u64 v[20:21], v[20:21], 0, s[60:61]
	global_load_dword v88, v[12:13], off offset:-4096 nt
	global_load_dword v89, v[14:15], off offset:-4096 nt
	global_load_dword v90, v[20:21], off offset:-4096 nt
	s_waitcnt vmcnt(52)
	v_lshlrev_b32_e32 v38, 16, v97
	v_and_b32_e32 v39, 0xffff0000, v97
	v_lshlrev_b32_e32 v42, 16, v99
	v_and_b32_e32 v43, 0xffff0000, v99
	v_pk_mul_f32 v[38:39], v[38:39], s[56:57] op_sel_hi:[1,0]
	v_pk_mul_f32 v[44:45], v[42:43], s[58:59] op_sel_hi:[1,0]
	v_lshlrev_b32_e32 v40, 16, v98
	v_and_b32_e32 v41, 0xffff0000, v98
	v_exp_f32_e32 v38, v38
	v_exp_f32_e32 v39, v39
	v_exp_f32_e32 v44, v44
	v_exp_f32_e32 v45, v45
	v_pk_add_f32 v[30:31], v[30:31], 1.0 op_sel_hi:[1,0]
	v_rcp_f32_e32 v30, v30
	v_rcp_f32_e32 v31, v31
	v_pk_fma_f32 v[6:7], v[6:7], v[24:25], v[26:27]
	v_pk_mul_f32 v[32:33], v[6:7], v[28:29]
	v_pk_mul_f32 v[32:33], v[32:33], v[30:31]
	v_cvt_pk_bf16_f32 v34, v32, v33
	global_store_dword v[22:23], v34, off offset:-1792
	global_load_dword v91, v[12:13], off offset:-3840 nt
	global_load_dword v92, v[14:15], off offset:-3840 nt
	global_load_dword v93, v[20:21], off offset:-3840 nt
	s_waitcnt vmcnt(52)
	v_lshlrev_b32_e32 v52, 16, v100
	v_and_b32_e32 v53, 0xffff0000, v100
	v_lshlrev_b32_e32 v56, 16, v102
	v_and_b32_e32 v57, 0xffff0000, v102
	v_pk_mul_f32 v[52:53], v[52:53], s[56:57] op_sel_hi:[1,0]
	v_pk_mul_f32 v[58:59], v[56:57], s[58:59] op_sel_hi:[1,0]
	v_lshlrev_b32_e32 v54, 16, v101
	v_and_b32_e32 v55, 0xffff0000, v101
	v_exp_f32_e32 v52, v52
	v_exp_f32_e32 v53, v53
	v_exp_f32_e32 v58, v58
	v_exp_f32_e32 v59, v59
	v_pk_add_f32 v[44:45], v[44:45], 1.0 op_sel_hi:[1,0]
	v_rcp_f32_e32 v44, v44
	v_rcp_f32_e32 v45, v45
	v_pk_fma_f32 v[6:7], v[6:7], v[38:39], v[40:41]
	v_pk_mul_f32 v[46:47], v[6:7], v[42:43]
	v_pk_mul_f32 v[46:47], v[46:47], v[44:45]
	v_cvt_pk_bf16_f32 v48, v46, v47
	global_store_dword v[22:23], v48, off offset:-1664
	global_load_dword v94, v[12:13], off offset:-3584 nt
	global_load_dword v95, v[14:15], off offset:-3584 nt
	global_load_dword v96, v[20:21], off offset:-3584 nt
	s_waitcnt vmcnt(52)
	v_lshlrev_b32_e32 v24, 16, v103
	v_and_b32_e32 v25, 0xffff0000, v103
	v_lshlrev_b32_e32 v28, 16, v105
	v_and_b32_e32 v29, 0xffff0000, v105
	v_pk_mul_f32 v[24:25], v[24:25], s[56:57] op_sel_hi:[1,0]
	v_pk_mul_f32 v[30:31], v[28:29], s[58:59] op_sel_hi:[1,0]
	v_lshlrev_b32_e32 v26, 16, v104
	v_and_b32_e32 v27, 0xffff0000, v104
	v_exp_f32_e32 v24, v24
	v_exp_f32_e32 v25, v25
	v_exp_f32_e32 v30, v30
	v_exp_f32_e32 v31, v31
	v_pk_add_f32 v[58:59], v[58:59], 1.0 op_sel_hi:[1,0]
	v_rcp_f32_e32 v58, v58
	v_rcp_f32_e32 v59, v59
	v_pk_fma_f32 v[6:7], v[6:7], v[52:53], v[54:55]
	v_pk_mul_f32 v[60:61], v[6:7], v[56:57]
	v_pk_mul_f32 v[60:61], v[60:61], v[58:59]
	v_cvt_pk_bf16_f32 v62, v60, v61
	global_store_dword v[22:23], v62, off offset:-1536
	global_load_dword v97, v[12:13], off offset:-3328 nt
	global_load_dword v98, v[14:15], off offset:-3328 nt
	global_load_dword v99, v[20:21], off offset:-3328 nt
	s_waitcnt vmcnt(52)
	v_lshlrev_b32_e32 v38, 16, v106
	v_and_b32_e32 v39, 0xffff0000, v106
	v_lshlrev_b32_e32 v42, 16, v108
	v_and_b32_e32 v43, 0xffff0000, v108
	v_pk_mul_f32 v[38:39], v[38:39], s[56:57] op_sel_hi:[1,0]
	v_pk_mul_f32 v[44:45], v[42:43], s[58:59] op_sel_hi:[1,0]
	v_lshlrev_b32_e32 v40, 16, v107
	v_and_b32_e32 v41, 0xffff0000, v107
	v_exp_f32_e32 v38, v38
	v_exp_f32_e32 v39, v39
	v_exp_f32_e32 v44, v44
	v_exp_f32_e32 v45, v45
	v_pk_add_f32 v[30:31], v[30:31], 1.0 op_sel_hi:[1,0]
	v_rcp_f32_e32 v30, v30
	v_rcp_f32_e32 v31, v31
	v_pk_fma_f32 v[6:7], v[6:7], v[24:25], v[26:27]
	v_pk_mul_f32 v[32:33], v[6:7], v[28:29]
	v_pk_mul_f32 v[32:33], v[32:33], v[30:31]
	v_cvt_pk_bf16_f32 v34, v32, v33
	global_store_dword v[22:23], v34, off offset:-1408
	global_load_dword v100, v[12:13], off offset:-3072 nt
	global_load_dword v101, v[14:15], off offset:-3072 nt
	global_load_dword v102, v[20:21], off offset:-3072 nt
	s_waitcnt vmcnt(52)
	v_lshlrev_b32_e32 v52, 16, v109
	v_and_b32_e32 v53, 0xffff0000, v109
	v_lshlrev_b32_e32 v56, 16, v111
	v_and_b32_e32 v57, 0xffff0000, v111
	v_pk_mul_f32 v[52:53], v[52:53], s[56:57] op_sel_hi:[1,0]
	v_pk_mul_f32 v[58:59], v[56:57], s[58:59] op_sel_hi:[1,0]
	v_lshlrev_b32_e32 v54, 16, v110
	v_and_b32_e32 v55, 0xffff0000, v110
	v_exp_f32_e32 v52, v52
	v_exp_f32_e32 v53, v53
	v_exp_f32_e32 v58, v58
	v_exp_f32_e32 v59, v59
	v_pk_add_f32 v[44:45], v[44:45], 1.0 op_sel_hi:[1,0]
	v_rcp_f32_e32 v44, v44
	v_rcp_f32_e32 v45, v45
	v_pk_fma_f32 v[6:7], v[6:7], v[38:39], v[40:41]
	v_pk_mul_f32 v[46:47], v[6:7], v[42:43]
	v_pk_mul_f32 v[46:47], v[46:47], v[44:45]
	v_cvt_pk_bf16_f32 v48, v46, v47
	global_store_dword v[22:23], v48, off offset:-1280
	global_load_dword v103, v[12:13], off offset:-2816 nt
	global_load_dword v104, v[14:15], off offset:-2816 nt
	global_load_dword v105, v[20:21], off offset:-2816 nt
	s_waitcnt vmcnt(52)
	v_lshlrev_b32_e32 v24, 16, v112
	v_and_b32_e32 v25, 0xffff0000, v112
	v_lshlrev_b32_e32 v28, 16, v114
	v_and_b32_e32 v29, 0xffff0000, v114
	v_pk_mul_f32 v[24:25], v[24:25], s[56:57] op_sel_hi:[1,0]
	v_pk_mul_f32 v[30:31], v[28:29], s[58:59] op_sel_hi:[1,0]
	v_lshlrev_b32_e32 v26, 16, v113
	v_and_b32_e32 v27, 0xffff0000, v113
	v_exp_f32_e32 v24, v24
	v_exp_f32_e32 v25, v25
	v_exp_f32_e32 v30, v30
	v_exp_f32_e32 v31, v31
	v_pk_add_f32 v[58:59], v[58:59], 1.0 op_sel_hi:[1,0]
	v_rcp_f32_e32 v58, v58
	v_rcp_f32_e32 v59, v59
	v_pk_fma_f32 v[6:7], v[6:7], v[52:53], v[54:55]
	v_pk_mul_f32 v[60:61], v[6:7], v[56:57]
	v_pk_mul_f32 v[60:61], v[60:61], v[58:59]
	v_cvt_pk_bf16_f32 v62, v60, v61
	global_store_dword v[22:23], v62, off offset:-1152
	global_load_dword v106, v[12:13], off offset:-2560 nt
	global_load_dword v107, v[14:15], off offset:-2560 nt
	global_load_dword v108, v[20:21], off offset:-2560 nt
	s_waitcnt vmcnt(52)
	v_lshlrev_b32_e32 v38, 16, v115
	v_and_b32_e32 v39, 0xffff0000, v115
	v_lshlrev_b32_e32 v42, 16, v117
	v_and_b32_e32 v43, 0xffff0000, v117
	v_pk_mul_f32 v[38:39], v[38:39], s[56:57] op_sel_hi:[1,0]
	v_pk_mul_f32 v[44:45], v[42:43], s[58:59] op_sel_hi:[1,0]
	v_lshlrev_b32_e32 v40, 16, v116
	v_and_b32_e32 v41, 0xffff0000, v116
	v_exp_f32_e32 v38, v38
	v_exp_f32_e32 v39, v39
	v_exp_f32_e32 v44, v44
	v_exp_f32_e32 v45, v45
	v_pk_add_f32 v[30:31], v[30:31], 1.0 op_sel_hi:[1,0]
	v_rcp_f32_e32 v30, v30
	v_rcp_f32_e32 v31, v31
	v_pk_fma_f32 v[6:7], v[6:7], v[24:25], v[26:27]
	v_pk_mul_f32 v[32:33], v[6:7], v[28:29]
	v_pk_mul_f32 v[32:33], v[32:33], v[30:31]
	v_cvt_pk_bf16_f32 v34, v32, v33
	global_store_dword v[22:23], v34, off offset:-1024
	global_load_dword v109, v[12:13], off offset:-2304 nt
	global_load_dword v110, v[14:15], off offset:-2304 nt
	global_load_dword v111, v[20:21], off offset:-2304 nt
	s_waitcnt vmcnt(52)
	v_lshlrev_b32_e32 v52, 16, v118
	v_and_b32_e32 v53, 0xffff0000, v118
	v_lshlrev_b32_e32 v56, 16, v120
	v_and_b32_e32 v57, 0xffff0000, v120
	v_pk_mul_f32 v[52:53], v[52:53], s[56:57] op_sel_hi:[1,0]
	v_pk_mul_f32 v[58:59], v[56:57], s[58:59] op_sel_hi:[1,0]
	v_lshlrev_b32_e32 v54, 16, v119
	v_and_b32_e32 v55, 0xffff0000, v119
	v_exp_f32_e32 v52, v52
	v_exp_f32_e32 v53, v53
	v_exp_f32_e32 v58, v58
	v_exp_f32_e32 v59, v59
	v_pk_add_f32 v[44:45], v[44:45], 1.0 op_sel_hi:[1,0]
	v_rcp_f32_e32 v44, v44
	v_rcp_f32_e32 v45, v45
	v_pk_fma_f32 v[6:7], v[6:7], v[38:39], v[40:41]
	v_pk_mul_f32 v[46:47], v[6:7], v[42:43]
	v_pk_mul_f32 v[46:47], v[46:47], v[44:45]
	v_cvt_pk_bf16_f32 v48, v46, v47
	global_store_dword v[22:23], v48, off offset:-896
	global_load_dword v112, v[12:13], off offset:-2048 nt
	global_load_dword v113, v[14:15], off offset:-2048 nt
	global_load_dword v114, v[20:21], off offset:-2048 nt
	s_waitcnt vmcnt(52)
	v_lshlrev_b32_e32 v24, 16, v121
	v_and_b32_e32 v25, 0xffff0000, v121
	v_lshlrev_b32_e32 v28, 16, v123
	v_and_b32_e32 v29, 0xffff0000, v123
	v_pk_mul_f32 v[24:25], v[24:25], s[56:57] op_sel_hi:[1,0]
	v_pk_mul_f32 v[30:31], v[28:29], s[58:59] op_sel_hi:[1,0]
	v_lshlrev_b32_e32 v26, 16, v122
	v_and_b32_e32 v27, 0xffff0000, v122
	v_exp_f32_e32 v24, v24
	v_exp_f32_e32 v25, v25
	v_exp_f32_e32 v30, v30
	v_exp_f32_e32 v31, v31
	v_pk_add_f32 v[58:59], v[58:59], 1.0 op_sel_hi:[1,0]
	v_rcp_f32_e32 v58, v58
	v_rcp_f32_e32 v59, v59
	v_pk_fma_f32 v[6:7], v[6:7], v[52:53], v[54:55]
	v_pk_mul_f32 v[60:61], v[6:7], v[56:57]
	v_pk_mul_f32 v[60:61], v[60:61], v[58:59]
	v_cvt_pk_bf16_f32 v62, v60, v61
	global_store_dword v[22:23], v62, off offset:-768
	global_load_dword v115, v[12:13], off offset:-1792 nt
	global_load_dword v116, v[14:15], off offset:-1792 nt
	global_load_dword v117, v[20:21], off offset:-1792 nt
	s_waitcnt vmcnt(52)
	v_lshlrev_b32_e32 v38, 16, v124
	v_and_b32_e32 v39, 0xffff0000, v124
	v_lshlrev_b32_e32 v42, 16, v126
	v_and_b32_e32 v43, 0xffff0000, v126
	v_pk_mul_f32 v[38:39], v[38:39], s[56:57] op_sel_hi:[1,0]
	v_pk_mul_f32 v[44:45], v[42:43], s[58:59] op_sel_hi:[1,0]
	v_lshlrev_b32_e32 v40, 16, v125
	v_and_b32_e32 v41, 0xffff0000, v125
	v_exp_f32_e32 v38, v38
	v_exp_f32_e32 v39, v39
	v_exp_f32_e32 v44, v44
	v_exp_f32_e32 v45, v45
	v_pk_add_f32 v[30:31], v[30:31], 1.0 op_sel_hi:[1,0]
	v_rcp_f32_e32 v30, v30
	v_rcp_f32_e32 v31, v31
	v_pk_fma_f32 v[6:7], v[6:7], v[24:25], v[26:27]
	v_pk_mul_f32 v[32:33], v[6:7], v[28:29]
	v_pk_mul_f32 v[32:33], v[32:33], v[30:31]
	v_cvt_pk_bf16_f32 v34, v32, v33
	global_store_dword v[22:23], v34, off offset:-640
	global_load_dword v118, v[12:13], off offset:-1536 nt
	global_load_dword v119, v[14:15], off offset:-1536 nt
	global_load_dword v120, v[20:21], off offset:-1536 nt
	s_waitcnt vmcnt(52)
	v_lshlrev_b32_e32 v52, 16, v127
	v_and_b32_e32 v53, 0xffff0000, v127
	v_lshlrev_b32_e32 v56, 16, v129
	v_and_b32_e32 v57, 0xffff0000, v129
	v_pk_mul_f32 v[52:53], v[52:53], s[56:57] op_sel_hi:[1,0]
	v_pk_mul_f32 v[58:59], v[56:57], s[58:59] op_sel_hi:[1,0]
	v_lshlrev_b32_e32 v54, 16, v128
	v_and_b32_e32 v55, 0xffff0000, v128
	v_exp_f32_e32 v52, v52
	v_exp_f32_e32 v53, v53
	v_exp_f32_e32 v58, v58
	v_exp_f32_e32 v59, v59
	v_pk_add_f32 v[44:45], v[44:45], 1.0 op_sel_hi:[1,0]
	v_rcp_f32_e32 v44, v44
	v_rcp_f32_e32 v45, v45
	v_pk_fma_f32 v[6:7], v[6:7], v[38:39], v[40:41]
	v_pk_mul_f32 v[46:47], v[6:7], v[42:43]
	v_pk_mul_f32 v[46:47], v[46:47], v[44:45]
	v_cvt_pk_bf16_f32 v48, v46, v47
	global_store_dword v[22:23], v48, off offset:-512
	global_load_dword v121, v[12:13], off offset:-1280 nt
	global_load_dword v122, v[14:15], off offset:-1280 nt
	global_load_dword v123, v[20:21], off offset:-1280 nt
	s_waitcnt vmcnt(52)
	v_lshlrev_b32_e32 v24, 16, v130
	v_and_b32_e32 v25, 0xffff0000, v130
	v_lshlrev_b32_e32 v28, 16, v132
	v_and_b32_e32 v29, 0xffff0000, v132
	v_pk_mul_f32 v[24:25], v[24:25], s[56:57] op_sel_hi:[1,0]
	v_pk_mul_f32 v[30:31], v[28:29], s[58:59] op_sel_hi:[1,0]
	v_lshlrev_b32_e32 v26, 16, v131
	v_and_b32_e32 v27, 0xffff0000, v131
	v_exp_f32_e32 v24, v24
	v_exp_f32_e32 v25, v25
	v_exp_f32_e32 v30, v30
	v_exp_f32_e32 v31, v31
	v_pk_add_f32 v[58:59], v[58:59], 1.0 op_sel_hi:[1,0]
	v_rcp_f32_e32 v58, v58
	v_rcp_f32_e32 v59, v59
	v_pk_fma_f32 v[6:7], v[6:7], v[52:53], v[54:55]
	v_pk_mul_f32 v[60:61], v[6:7], v[56:57]
	v_pk_mul_f32 v[60:61], v[60:61], v[58:59]
	v_cvt_pk_bf16_f32 v62, v60, v61
	global_store_dword v[22:23], v62, off offset:-384
	global_load_dword v124, v[12:13], off offset:-1024 nt
	global_load_dword v125, v[14:15], off offset:-1024 nt
	global_load_dword v126, v[20:21], off offset:-1024 nt
	s_waitcnt vmcnt(52)
	v_lshlrev_b32_e32 v38, 16, v133
	v_and_b32_e32 v39, 0xffff0000, v133
	v_lshlrev_b32_e32 v42, 16, v135
	v_and_b32_e32 v43, 0xffff0000, v135
	v_pk_mul_f32 v[38:39], v[38:39], s[56:57] op_sel_hi:[1,0]
	v_pk_mul_f32 v[44:45], v[42:43], s[58:59] op_sel_hi:[1,0]
	v_lshlrev_b32_e32 v40, 16, v134
	v_and_b32_e32 v41, 0xffff0000, v134
	v_exp_f32_e32 v38, v38
	v_exp_f32_e32 v39, v39
	v_exp_f32_e32 v44, v44
	v_exp_f32_e32 v45, v45
	v_pk_add_f32 v[30:31], v[30:31], 1.0 op_sel_hi:[1,0]
	v_rcp_f32_e32 v30, v30
	v_rcp_f32_e32 v31, v31
	v_pk_fma_f32 v[6:7], v[6:7], v[24:25], v[26:27]
	v_pk_mul_f32 v[32:33], v[6:7], v[28:29]
	v_pk_mul_f32 v[32:33], v[32:33], v[30:31]
	v_cvt_pk_bf16_f32 v34, v32, v33
	global_store_dword v[22:23], v34, off offset:-256
	global_load_dword v127, v[12:13], off offset:-768 nt
	global_load_dword v128, v[14:15], off offset:-768 nt
	global_load_dword v129, v[20:21], off offset:-768 nt
	s_waitcnt vmcnt(52)
	v_lshlrev_b32_e32 v52, 16, v88
	v_and_b32_e32 v53, 0xffff0000, v88
	v_lshlrev_b32_e32 v56, 16, v90
	v_and_b32_e32 v57, 0xffff0000, v90
	v_pk_mul_f32 v[52:53], v[52:53], s[56:57] op_sel_hi:[1,0]
	v_pk_mul_f32 v[58:59], v[56:57], s[58:59] op_sel_hi:[1,0]
	v_lshlrev_b32_e32 v54, 16, v89
	v_and_b32_e32 v55, 0xffff0000, v89
	v_exp_f32_e32 v52, v52
	v_exp_f32_e32 v53, v53
	v_exp_f32_e32 v58, v58
	v_exp_f32_e32 v59, v59
	v_pk_add_f32 v[44:45], v[44:45], 1.0 op_sel_hi:[1,0]
	v_rcp_f32_e32 v44, v44
	v_rcp_f32_e32 v45, v45
	v_pk_fma_f32 v[6:7], v[6:7], v[38:39], v[40:41]
	v_pk_mul_f32 v[46:47], v[6:7], v[42:43]
	v_pk_mul_f32 v[46:47], v[46:47], v[44:45]
	v_cvt_pk_bf16_f32 v48, v46, v47
	global_store_dword v[22:23], v48, off offset:-128
	global_load_dword v130, v[12:13], off offset:-512 nt
	global_load_dword v131, v[14:15], off offset:-512 nt
	global_load_dword v132, v[20:21], off offset:-512 nt
	s_waitcnt vmcnt(52)
	v_lshlrev_b32_e32 v24, 16, v91
	v_and_b32_e32 v25, 0xffff0000, v91
	v_lshlrev_b32_e32 v28, 16, v93
	v_and_b32_e32 v29, 0xffff0000, v93
	v_pk_mul_f32 v[24:25], v[24:25], s[56:57] op_sel_hi:[1,0]
	v_pk_mul_f32 v[30:31], v[28:29], s[58:59] op_sel_hi:[1,0]
	v_lshlrev_b32_e32 v26, 16, v92
	v_and_b32_e32 v27, 0xffff0000, v92
	v_exp_f32_e32 v24, v24
	v_exp_f32_e32 v25, v25
	v_exp_f32_e32 v30, v30
	v_exp_f32_e32 v31, v31
	v_pk_add_f32 v[58:59], v[58:59], 1.0 op_sel_hi:[1,0]
	v_rcp_f32_e32 v58, v58
	v_rcp_f32_e32 v59, v59
	v_pk_fma_f32 v[6:7], v[6:7], v[52:53], v[54:55]
	v_pk_mul_f32 v[60:61], v[6:7], v[56:57]
	v_pk_mul_f32 v[60:61], v[60:61], v[58:59]
	v_cvt_pk_bf16_f32 v62, v60, v61
	global_store_dword v[22:23], v62, off
	global_load_dword v133, v[12:13], off offset:-256 nt
	global_load_dword v134, v[14:15], off offset:-256 nt
	global_load_dword v135, v[20:21], off offset:-256 nt
	s_waitcnt vmcnt(52)
	v_lshlrev_b32_e32 v38, 16, v94
	v_and_b32_e32 v39, 0xffff0000, v94
	v_lshlrev_b32_e32 v42, 16, v96
	v_and_b32_e32 v43, 0xffff0000, v96
	v_pk_mul_f32 v[38:39], v[38:39], s[56:57] op_sel_hi:[1,0]
	v_pk_mul_f32 v[44:45], v[42:43], s[58:59] op_sel_hi:[1,0]
	v_lshlrev_b32_e32 v40, 16, v95
	v_and_b32_e32 v41, 0xffff0000, v95
	v_exp_f32_e32 v38, v38
	v_exp_f32_e32 v39, v39
	v_exp_f32_e32 v44, v44
	v_exp_f32_e32 v45, v45
	v_pk_add_f32 v[30:31], v[30:31], 1.0 op_sel_hi:[1,0]
	v_rcp_f32_e32 v30, v30
	v_rcp_f32_e32 v31, v31
	v_pk_fma_f32 v[6:7], v[6:7], v[24:25], v[26:27]
	v_pk_mul_f32 v[32:33], v[6:7], v[28:29]
	v_pk_mul_f32 v[32:33], v[32:33], v[30:31]
	v_cvt_pk_bf16_f32 v34, v32, v33
	global_store_dword v[22:23], v34, off offset:128
	global_load_dword v88, v[12:13], off nt
	global_load_dword v89, v[14:15], off nt
	global_load_dword v90, v[20:21], off nt
	s_waitcnt vmcnt(52)
	v_lshlrev_b32_e32 v52, 16, v97
	v_and_b32_e32 v53, 0xffff0000, v97
	v_lshlrev_b32_e32 v56, 16, v99
	v_and_b32_e32 v57, 0xffff0000, v99
	v_pk_mul_f32 v[52:53], v[52:53], s[56:57] op_sel_hi:[1,0]
	v_pk_mul_f32 v[58:59], v[56:57], s[58:59] op_sel_hi:[1,0]
	v_lshlrev_b32_e32 v54, 16, v98
	v_and_b32_e32 v55, 0xffff0000, v98
	v_exp_f32_e32 v52, v52
	v_exp_f32_e32 v53, v53
	v_exp_f32_e32 v58, v58
	v_exp_f32_e32 v59, v59
	v_pk_add_f32 v[44:45], v[44:45], 1.0 op_sel_hi:[1,0]
	v_rcp_f32_e32 v44, v44
	v_rcp_f32_e32 v45, v45
	v_pk_fma_f32 v[6:7], v[6:7], v[38:39], v[40:41]
	v_pk_mul_f32 v[46:47], v[6:7], v[42:43]
	v_pk_mul_f32 v[46:47], v[46:47], v[44:45]
	v_cvt_pk_bf16_f32 v48, v46, v47
	global_store_dword v[22:23], v48, off offset:256
	global_load_dword v91, v[12:13], off offset:256 nt
	global_load_dword v92, v[14:15], off offset:256 nt
	global_load_dword v93, v[20:21], off offset:256 nt
	s_waitcnt vmcnt(52)
	v_lshlrev_b32_e32 v24, 16, v100
	v_and_b32_e32 v25, 0xffff0000, v100
	v_lshlrev_b32_e32 v28, 16, v102
	v_and_b32_e32 v29, 0xffff0000, v102
	v_pk_mul_f32 v[24:25], v[24:25], s[56:57] op_sel_hi:[1,0]
	v_pk_mul_f32 v[30:31], v[28:29], s[58:59] op_sel_hi:[1,0]
	v_lshlrev_b32_e32 v26, 16, v101
	v_and_b32_e32 v27, 0xffff0000, v101
	v_exp_f32_e32 v24, v24
	v_exp_f32_e32 v25, v25
	v_exp_f32_e32 v30, v30
	v_exp_f32_e32 v31, v31
	v_pk_add_f32 v[58:59], v[58:59], 1.0 op_sel_hi:[1,0]
	v_rcp_f32_e32 v58, v58
	v_rcp_f32_e32 v59, v59
	v_pk_fma_f32 v[6:7], v[6:7], v[52:53], v[54:55]
	v_pk_mul_f32 v[60:61], v[6:7], v[56:57]
	v_pk_mul_f32 v[60:61], v[60:61], v[58:59]
	v_cvt_pk_bf16_f32 v62, v60, v61
	global_store_dword v[22:23], v62, off offset:384
	global_load_dword v94, v[12:13], off offset:512 nt
	global_load_dword v95, v[14:15], off offset:512 nt
	global_load_dword v96, v[20:21], off offset:512 nt
	s_waitcnt vmcnt(52)
	v_lshlrev_b32_e32 v38, 16, v103
	v_and_b32_e32 v39, 0xffff0000, v103
	v_lshlrev_b32_e32 v42, 16, v105
	v_and_b32_e32 v43, 0xffff0000, v105
	v_pk_mul_f32 v[38:39], v[38:39], s[56:57] op_sel_hi:[1,0]
	v_pk_mul_f32 v[44:45], v[42:43], s[58:59] op_sel_hi:[1,0]
	v_lshlrev_b32_e32 v40, 16, v104
	v_and_b32_e32 v41, 0xffff0000, v104
	v_exp_f32_e32 v38, v38
	v_exp_f32_e32 v39, v39
	v_exp_f32_e32 v44, v44
	v_exp_f32_e32 v45, v45
	v_pk_add_f32 v[30:31], v[30:31], 1.0 op_sel_hi:[1,0]
	v_rcp_f32_e32 v30, v30
	v_rcp_f32_e32 v31, v31
	v_pk_fma_f32 v[6:7], v[6:7], v[24:25], v[26:27]
	v_pk_mul_f32 v[32:33], v[6:7], v[28:29]
	v_pk_mul_f32 v[32:33], v[32:33], v[30:31]
	v_cvt_pk_bf16_f32 v34, v32, v33
	global_store_dword v[22:23], v34, off offset:512
	global_load_dword v97, v[12:13], off offset:768 nt
	global_load_dword v98, v[14:15], off offset:768 nt
	global_load_dword v99, v[20:21], off offset:768 nt
	s_waitcnt vmcnt(52)
	v_lshlrev_b32_e32 v52, 16, v106
	v_and_b32_e32 v53, 0xffff0000, v106
	v_lshlrev_b32_e32 v56, 16, v108
	v_and_b32_e32 v57, 0xffff0000, v108
	v_pk_mul_f32 v[52:53], v[52:53], s[56:57] op_sel_hi:[1,0]
	v_pk_mul_f32 v[58:59], v[56:57], s[58:59] op_sel_hi:[1,0]
	v_lshlrev_b32_e32 v54, 16, v107
	v_and_b32_e32 v55, 0xffff0000, v107
	v_exp_f32_e32 v52, v52
	v_exp_f32_e32 v53, v53
	v_exp_f32_e32 v58, v58
	v_exp_f32_e32 v59, v59
	v_pk_add_f32 v[44:45], v[44:45], 1.0 op_sel_hi:[1,0]
	v_rcp_f32_e32 v44, v44
	v_rcp_f32_e32 v45, v45
	v_pk_fma_f32 v[6:7], v[6:7], v[38:39], v[40:41]
	v_pk_mul_f32 v[46:47], v[6:7], v[42:43]
	v_pk_mul_f32 v[46:47], v[46:47], v[44:45]
	v_cvt_pk_bf16_f32 v48, v46, v47
	global_store_dword v[22:23], v48, off offset:640
	global_load_dword v100, v[12:13], off offset:1024 nt
	global_load_dword v101, v[14:15], off offset:1024 nt
	global_load_dword v102, v[20:21], off offset:1024 nt
	s_waitcnt vmcnt(52)
	v_lshlrev_b32_e32 v24, 16, v109
	v_and_b32_e32 v25, 0xffff0000, v109
	v_lshlrev_b32_e32 v28, 16, v111
	v_and_b32_e32 v29, 0xffff0000, v111
	v_pk_mul_f32 v[24:25], v[24:25], s[56:57] op_sel_hi:[1,0]
	v_pk_mul_f32 v[30:31], v[28:29], s[58:59] op_sel_hi:[1,0]
	v_lshlrev_b32_e32 v26, 16, v110
	v_and_b32_e32 v27, 0xffff0000, v110
	v_exp_f32_e32 v24, v24
	v_exp_f32_e32 v25, v25
	v_exp_f32_e32 v30, v30
	v_exp_f32_e32 v31, v31
	v_pk_add_f32 v[58:59], v[58:59], 1.0 op_sel_hi:[1,0]
	v_rcp_f32_e32 v58, v58
	v_rcp_f32_e32 v59, v59
	v_pk_fma_f32 v[6:7], v[6:7], v[52:53], v[54:55]
	v_pk_mul_f32 v[60:61], v[6:7], v[56:57]
	v_pk_mul_f32 v[60:61], v[60:61], v[58:59]
	v_cvt_pk_bf16_f32 v62, v60, v61
	global_store_dword v[22:23], v62, off offset:768
	global_load_dword v103, v[12:13], off offset:1280 nt
	global_load_dword v104, v[14:15], off offset:1280 nt
	global_load_dword v105, v[20:21], off offset:1280 nt
	s_waitcnt vmcnt(52)
	v_lshlrev_b32_e32 v38, 16, v112
	v_and_b32_e32 v39, 0xffff0000, v112
	v_lshlrev_b32_e32 v42, 16, v114
	v_and_b32_e32 v43, 0xffff0000, v114
	v_pk_mul_f32 v[38:39], v[38:39], s[56:57] op_sel_hi:[1,0]
	v_pk_mul_f32 v[44:45], v[42:43], s[58:59] op_sel_hi:[1,0]
	v_lshlrev_b32_e32 v40, 16, v113
	v_and_b32_e32 v41, 0xffff0000, v113
	v_exp_f32_e32 v38, v38
	v_exp_f32_e32 v39, v39
	v_exp_f32_e32 v44, v44
	v_exp_f32_e32 v45, v45
	v_pk_add_f32 v[30:31], v[30:31], 1.0 op_sel_hi:[1,0]
	v_rcp_f32_e32 v30, v30
	v_rcp_f32_e32 v31, v31
	v_pk_fma_f32 v[6:7], v[6:7], v[24:25], v[26:27]
	v_pk_mul_f32 v[32:33], v[6:7], v[28:29]
	v_pk_mul_f32 v[32:33], v[32:33], v[30:31]
	v_cvt_pk_bf16_f32 v34, v32, v33
	global_store_dword v[22:23], v34, off offset:896
	global_load_dword v106, v[12:13], off offset:1536 nt
	global_load_dword v107, v[14:15], off offset:1536 nt
	global_load_dword v108, v[20:21], off offset:1536 nt
	s_waitcnt vmcnt(52)
	v_lshlrev_b32_e32 v52, 16, v115
	v_and_b32_e32 v53, 0xffff0000, v115
	v_lshlrev_b32_e32 v56, 16, v117
	v_and_b32_e32 v57, 0xffff0000, v117
	v_pk_mul_f32 v[52:53], v[52:53], s[56:57] op_sel_hi:[1,0]
	v_pk_mul_f32 v[58:59], v[56:57], s[58:59] op_sel_hi:[1,0]
	v_lshlrev_b32_e32 v54, 16, v116
	v_and_b32_e32 v55, 0xffff0000, v116
	v_exp_f32_e32 v52, v52
	v_exp_f32_e32 v53, v53
	v_exp_f32_e32 v58, v58
	v_exp_f32_e32 v59, v59
	v_pk_add_f32 v[44:45], v[44:45], 1.0 op_sel_hi:[1,0]
	v_rcp_f32_e32 v44, v44
	v_rcp_f32_e32 v45, v45
	v_pk_fma_f32 v[6:7], v[6:7], v[38:39], v[40:41]
	v_pk_mul_f32 v[46:47], v[6:7], v[42:43]
	v_pk_mul_f32 v[46:47], v[46:47], v[44:45]
	v_cvt_pk_bf16_f32 v48, v46, v47
	global_store_dword v[22:23], v48, off offset:1024
	global_load_dword v109, v[12:13], off offset:1792 nt
	global_load_dword v110, v[14:15], off offset:1792 nt
	global_load_dword v111, v[20:21], off offset:1792 nt
	s_waitcnt vmcnt(52)
	v_lshlrev_b32_e32 v24, 16, v118
	v_and_b32_e32 v25, 0xffff0000, v118
	v_lshlrev_b32_e32 v28, 16, v120
	v_and_b32_e32 v29, 0xffff0000, v120
	v_pk_mul_f32 v[24:25], v[24:25], s[56:57] op_sel_hi:[1,0]
	v_pk_mul_f32 v[30:31], v[28:29], s[58:59] op_sel_hi:[1,0]
	v_lshlrev_b32_e32 v26, 16, v119
	v_and_b32_e32 v27, 0xffff0000, v119
	v_exp_f32_e32 v24, v24
	v_exp_f32_e32 v25, v25
	v_exp_f32_e32 v30, v30
	v_exp_f32_e32 v31, v31
	v_pk_add_f32 v[58:59], v[58:59], 1.0 op_sel_hi:[1,0]
	v_rcp_f32_e32 v58, v58
	v_rcp_f32_e32 v59, v59
	v_pk_fma_f32 v[6:7], v[6:7], v[52:53], v[54:55]
	v_pk_mul_f32 v[60:61], v[6:7], v[56:57]
	v_pk_mul_f32 v[60:61], v[60:61], v[58:59]
	v_cvt_pk_bf16_f32 v62, v60, v61
	global_store_dword v[22:23], v62, off offset:1152
	global_load_dword v112, v[12:13], off offset:2048 nt
	global_load_dword v113, v[14:15], off offset:2048 nt
	global_load_dword v114, v[20:21], off offset:2048 nt
	s_waitcnt vmcnt(52)
	v_lshlrev_b32_e32 v38, 16, v121
	v_and_b32_e32 v39, 0xffff0000, v121
	v_lshlrev_b32_e32 v42, 16, v123
	v_and_b32_e32 v43, 0xffff0000, v123
	v_pk_mul_f32 v[38:39], v[38:39], s[56:57] op_sel_hi:[1,0]
	v_pk_mul_f32 v[44:45], v[42:43], s[58:59] op_sel_hi:[1,0]
	v_lshlrev_b32_e32 v40, 16, v122
	v_and_b32_e32 v41, 0xffff0000, v122
	v_exp_f32_e32 v38, v38
	v_exp_f32_e32 v39, v39
	v_exp_f32_e32 v44, v44
	v_exp_f32_e32 v45, v45
	v_pk_add_f32 v[30:31], v[30:31], 1.0 op_sel_hi:[1,0]
	v_rcp_f32_e32 v30, v30
	v_rcp_f32_e32 v31, v31
	v_pk_fma_f32 v[6:7], v[6:7], v[24:25], v[26:27]
	v_pk_mul_f32 v[32:33], v[6:7], v[28:29]
	v_pk_mul_f32 v[32:33], v[32:33], v[30:31]
	v_cvt_pk_bf16_f32 v34, v32, v33
	global_store_dword v[22:23], v34, off offset:1280
	global_load_dword v115, v[12:13], off offset:2304 nt
	global_load_dword v116, v[14:15], off offset:2304 nt
	global_load_dword v117, v[20:21], off offset:2304 nt
	s_waitcnt vmcnt(52)
	v_lshlrev_b32_e32 v52, 16, v124
	v_and_b32_e32 v53, 0xffff0000, v124
	v_lshlrev_b32_e32 v56, 16, v126
	v_and_b32_e32 v57, 0xffff0000, v126
	v_pk_mul_f32 v[52:53], v[52:53], s[56:57] op_sel_hi:[1,0]
	v_pk_mul_f32 v[58:59], v[56:57], s[58:59] op_sel_hi:[1,0]
	v_lshlrev_b32_e32 v54, 16, v125
	v_and_b32_e32 v55, 0xffff0000, v125
	v_exp_f32_e32 v52, v52
	v_exp_f32_e32 v53, v53
	v_exp_f32_e32 v58, v58
	v_exp_f32_e32 v59, v59
	v_pk_add_f32 v[44:45], v[44:45], 1.0 op_sel_hi:[1,0]
	v_rcp_f32_e32 v44, v44
	v_rcp_f32_e32 v45, v45
	v_pk_fma_f32 v[6:7], v[6:7], v[38:39], v[40:41]
	v_pk_mul_f32 v[46:47], v[6:7], v[42:43]
	v_pk_mul_f32 v[46:47], v[46:47], v[44:45]
	v_cvt_pk_bf16_f32 v48, v46, v47
	global_store_dword v[22:23], v48, off offset:1408
	global_load_dword v118, v[12:13], off offset:2560 nt
	global_load_dword v119, v[14:15], off offset:2560 nt
	global_load_dword v120, v[20:21], off offset:2560 nt
	s_waitcnt vmcnt(52)
	v_lshlrev_b32_e32 v24, 16, v127
	v_and_b32_e32 v25, 0xffff0000, v127
	v_lshlrev_b32_e32 v28, 16, v129
	v_and_b32_e32 v29, 0xffff0000, v129
	v_pk_mul_f32 v[24:25], v[24:25], s[56:57] op_sel_hi:[1,0]
	v_pk_mul_f32 v[30:31], v[28:29], s[58:59] op_sel_hi:[1,0]
	v_lshlrev_b32_e32 v26, 16, v128
	v_and_b32_e32 v27, 0xffff0000, v128
	v_exp_f32_e32 v24, v24
	v_exp_f32_e32 v25, v25
	v_exp_f32_e32 v30, v30
	v_exp_f32_e32 v31, v31
	v_pk_add_f32 v[58:59], v[58:59], 1.0 op_sel_hi:[1,0]
	v_rcp_f32_e32 v58, v58
	v_rcp_f32_e32 v59, v59
	v_pk_fma_f32 v[6:7], v[6:7], v[52:53], v[54:55]
	v_pk_mul_f32 v[60:61], v[6:7], v[56:57]
	v_pk_mul_f32 v[60:61], v[60:61], v[58:59]
	v_cvt_pk_bf16_f32 v62, v60, v61
	global_store_dword v[22:23], v62, off offset:1536
	global_load_dword v121, v[12:13], off offset:2816 nt
	global_load_dword v122, v[14:15], off offset:2816 nt
	global_load_dword v123, v[20:21], off offset:2816 nt
	s_waitcnt vmcnt(52)
	v_lshlrev_b32_e32 v38, 16, v130
	v_and_b32_e32 v39, 0xffff0000, v130
	v_lshlrev_b32_e32 v42, 16, v132
	v_and_b32_e32 v43, 0xffff0000, v132
	v_pk_mul_f32 v[38:39], v[38:39], s[56:57] op_sel_hi:[1,0]
	v_pk_mul_f32 v[44:45], v[42:43], s[58:59] op_sel_hi:[1,0]
	v_lshlrev_b32_e32 v40, 16, v131
	v_and_b32_e32 v41, 0xffff0000, v131
	v_exp_f32_e32 v38, v38
	v_exp_f32_e32 v39, v39
	v_exp_f32_e32 v44, v44
	v_exp_f32_e32 v45, v45
	v_pk_add_f32 v[30:31], v[30:31], 1.0 op_sel_hi:[1,0]
	v_rcp_f32_e32 v30, v30
	v_rcp_f32_e32 v31, v31
	v_pk_fma_f32 v[6:7], v[6:7], v[24:25], v[26:27]
	v_pk_mul_f32 v[32:33], v[6:7], v[28:29]
	v_pk_mul_f32 v[32:33], v[32:33], v[30:31]
	v_cvt_pk_bf16_f32 v34, v32, v33
	global_store_dword v[22:23], v34, off offset:1664
	global_load_dword v124, v[12:13], off offset:3072 nt
	global_load_dword v125, v[14:15], off offset:3072 nt
	global_load_dword v126, v[20:21], off offset:3072 nt
	s_waitcnt vmcnt(52)
	v_lshlrev_b32_e32 v52, 16, v133
	v_and_b32_e32 v53, 0xffff0000, v133
	v_lshlrev_b32_e32 v56, 16, v135
	v_and_b32_e32 v57, 0xffff0000, v135
	v_pk_mul_f32 v[52:53], v[52:53], s[56:57] op_sel_hi:[1,0]
	v_pk_mul_f32 v[58:59], v[56:57], s[58:59] op_sel_hi:[1,0]
	v_lshlrev_b32_e32 v54, 16, v134
	v_and_b32_e32 v55, 0xffff0000, v134
	v_exp_f32_e32 v52, v52
	v_exp_f32_e32 v53, v53
	v_exp_f32_e32 v58, v58
	v_exp_f32_e32 v59, v59
	v_pk_add_f32 v[44:45], v[44:45], 1.0 op_sel_hi:[1,0]
	v_rcp_f32_e32 v44, v44
	v_rcp_f32_e32 v45, v45
	v_pk_fma_f32 v[6:7], v[6:7], v[38:39], v[40:41]
	v_pk_mul_f32 v[46:47], v[6:7], v[42:43]
	v_pk_mul_f32 v[46:47], v[46:47], v[44:45]
	v_cvt_pk_bf16_f32 v48, v46, v47
	global_store_dword v[22:23], v48, off offset:1792
	global_load_dword v127, v[12:13], off offset:3328 nt
	global_load_dword v128, v[14:15], off offset:3328 nt
	global_load_dword v129, v[20:21], off offset:3328 nt
	s_waitcnt vmcnt(52)
	v_lshlrev_b32_e32 v24, 16, v88
	v_and_b32_e32 v25, 0xffff0000, v88
	v_lshlrev_b32_e32 v28, 16, v90
	v_and_b32_e32 v29, 0xffff0000, v90
	v_pk_mul_f32 v[24:25], v[24:25], s[56:57] op_sel_hi:[1,0]
	v_pk_mul_f32 v[30:31], v[28:29], s[58:59] op_sel_hi:[1,0]
	v_lshlrev_b32_e32 v26, 16, v89
	v_and_b32_e32 v27, 0xffff0000, v89
	v_exp_f32_e32 v24, v24
	v_exp_f32_e32 v25, v25
	v_exp_f32_e32 v30, v30
	v_exp_f32_e32 v31, v31
	v_pk_add_f32 v[58:59], v[58:59], 1.0 op_sel_hi:[1,0]
	v_rcp_f32_e32 v58, v58
	v_rcp_f32_e32 v59, v59
	v_pk_fma_f32 v[6:7], v[6:7], v[52:53], v[54:55]
	v_pk_mul_f32 v[60:61], v[6:7], v[56:57]
	v_pk_mul_f32 v[60:61], v[60:61], v[58:59]
	v_cvt_pk_bf16_f32 v62, v60, v61
	global_store_dword v[22:23], v62, off offset:1920
	global_load_dword v130, v[12:13], off offset:3584 nt
	global_load_dword v131, v[14:15], off offset:3584 nt
	global_load_dword v132, v[20:21], off offset:3584 nt
	s_waitcnt vmcnt(52)
	v_lshlrev_b32_e32 v38, 16, v91
	v_and_b32_e32 v39, 0xffff0000, v91
	v_lshlrev_b32_e32 v42, 16, v93
	v_and_b32_e32 v43, 0xffff0000, v93
	v_pk_mul_f32 v[38:39], v[38:39], s[56:57] op_sel_hi:[1,0]
	v_pk_mul_f32 v[44:45], v[42:43], s[58:59] op_sel_hi:[1,0]
	v_lshlrev_b32_e32 v40, 16, v92
	v_and_b32_e32 v41, 0xffff0000, v92
	v_exp_f32_e32 v38, v38
	v_exp_f32_e32 v39, v39
	v_exp_f32_e32 v44, v44
	v_exp_f32_e32 v45, v45
	v_pk_add_f32 v[30:31], v[30:31], 1.0 op_sel_hi:[1,0]
	v_rcp_f32_e32 v30, v30
	v_rcp_f32_e32 v31, v31
	v_pk_fma_f32 v[6:7], v[6:7], v[24:25], v[26:27]
	v_pk_mul_f32 v[32:33], v[6:7], v[28:29]
	v_pk_mul_f32 v[32:33], v[32:33], v[30:31]
	v_cvt_pk_bf16_f32 v34, v32, v33
	global_store_dword v[22:23], v34, off offset:2048
	global_load_dword v133, v[12:13], off offset:3840 nt
	global_load_dword v134, v[14:15], off offset:3840 nt
	global_load_dword v135, v[20:21], off offset:3840 nt
	s_waitcnt vmcnt(52)
	v_lshlrev_b32_e32 v52, 16, v94
	v_and_b32_e32 v53, 0xffff0000, v94
	v_lshlrev_b32_e32 v56, 16, v96
	v_and_b32_e32 v57, 0xffff0000, v96
	v_pk_mul_f32 v[52:53], v[52:53], s[56:57] op_sel_hi:[1,0]
	v_pk_mul_f32 v[58:59], v[56:57], s[58:59] op_sel_hi:[1,0]
	v_lshlrev_b32_e32 v54, 16, v95
	v_and_b32_e32 v55, 0xffff0000, v95
	v_exp_f32_e32 v52, v52
	v_exp_f32_e32 v53, v53
	v_exp_f32_e32 v58, v58
	v_exp_f32_e32 v59, v59
	v_pk_add_f32 v[44:45], v[44:45], 1.0 op_sel_hi:[1,0]
	v_rcp_f32_e32 v44, v44
	v_rcp_f32_e32 v45, v45
	v_pk_fma_f32 v[6:7], v[6:7], v[38:39], v[40:41]
	v_pk_mul_f32 v[46:47], v[6:7], v[42:43]
	v_pk_mul_f32 v[46:47], v[46:47], v[44:45]
	v_cvt_pk_bf16_f32 v48, v46, v47
	global_store_dword v[22:23], v48, off offset:2176
	v_lshl_add_u64 v[12:13], v[12:13], 0, s[60:61]
	v_lshl_add_u64 v[12:13], v[12:13], 0, s[60:61]
	v_lshl_add_u64 v[14:15], v[14:15], 0, s[60:61]
	v_lshl_add_u64 v[14:15], v[14:15], 0, s[60:61]
	v_lshl_add_u64 v[20:21], v[20:21], 0, s[60:61]
	v_lshl_add_u64 v[20:21], v[20:21], 0, s[60:61]
	global_load_dword v88, v[12:13], off offset:-4096 nt
	global_load_dword v89, v[14:15], off offset:-4096 nt
	global_load_dword v90, v[20:21], off offset:-4096 nt
	s_waitcnt vmcnt(52)
	v_lshlrev_b32_e32 v24, 16, v97
	v_and_b32_e32 v25, 0xffff0000, v97
	v_lshlrev_b32_e32 v28, 16, v99
	v_and_b32_e32 v29, 0xffff0000, v99
	v_pk_mul_f32 v[24:25], v[24:25], s[56:57] op_sel_hi:[1,0]
	v_pk_mul_f32 v[30:31], v[28:29], s[58:59] op_sel_hi:[1,0]
	v_lshlrev_b32_e32 v26, 16, v98
	v_and_b32_e32 v27, 0xffff0000, v98
	v_exp_f32_e32 v24, v24
	v_exp_f32_e32 v25, v25
	v_exp_f32_e32 v30, v30
	v_exp_f32_e32 v31, v31
	v_pk_add_f32 v[58:59], v[58:59], 1.0 op_sel_hi:[1,0]
	v_rcp_f32_e32 v58, v58
	v_rcp_f32_e32 v59, v59
	v_pk_fma_f32 v[6:7], v[6:7], v[52:53], v[54:55]
	v_pk_mul_f32 v[60:61], v[6:7], v[56:57]
	v_pk_mul_f32 v[60:61], v[60:61], v[58:59]
	v_cvt_pk_bf16_f32 v62, v60, v61
	global_store_dword v[22:23], v62, off offset:2304
	global_load_dword v91, v[12:13], off offset:-3840 nt
	global_load_dword v92, v[14:15], off offset:-3840 nt
	global_load_dword v93, v[20:21], off offset:-3840 nt
	s_waitcnt vmcnt(52)
	v_lshlrev_b32_e32 v38, 16, v100
	v_and_b32_e32 v39, 0xffff0000, v100
	v_lshlrev_b32_e32 v42, 16, v102
	v_and_b32_e32 v43, 0xffff0000, v102
	v_pk_mul_f32 v[38:39], v[38:39], s[56:57] op_sel_hi:[1,0]
	v_pk_mul_f32 v[44:45], v[42:43], s[58:59] op_sel_hi:[1,0]
	v_lshlrev_b32_e32 v40, 16, v101
	v_and_b32_e32 v41, 0xffff0000, v101
	v_exp_f32_e32 v38, v38
	v_exp_f32_e32 v39, v39
	v_exp_f32_e32 v44, v44
	v_exp_f32_e32 v45, v45
	v_pk_add_f32 v[30:31], v[30:31], 1.0 op_sel_hi:[1,0]
	v_rcp_f32_e32 v30, v30
	v_rcp_f32_e32 v31, v31
	v_pk_fma_f32 v[6:7], v[6:7], v[24:25], v[26:27]
	v_pk_mul_f32 v[32:33], v[6:7], v[28:29]
	v_pk_mul_f32 v[32:33], v[32:33], v[30:31]
	v_cvt_pk_bf16_f32 v34, v32, v33
	global_store_dword v[22:23], v34, off offset:2432
	global_load_dword v94, v[12:13], off offset:-3584 nt
	global_load_dword v95, v[14:15], off offset:-3584 nt
	global_load_dword v96, v[20:21], off offset:-3584 nt
	s_waitcnt vmcnt(52)
	v_lshlrev_b32_e32 v52, 16, v103
	v_and_b32_e32 v53, 0xffff0000, v103
	v_lshlrev_b32_e32 v56, 16, v105
	v_and_b32_e32 v57, 0xffff0000, v105
	v_pk_mul_f32 v[52:53], v[52:53], s[56:57] op_sel_hi:[1,0]
	v_pk_mul_f32 v[58:59], v[56:57], s[58:59] op_sel_hi:[1,0]
	v_lshlrev_b32_e32 v54, 16, v104
	v_and_b32_e32 v55, 0xffff0000, v104
	v_exp_f32_e32 v52, v52
	v_exp_f32_e32 v53, v53
	v_exp_f32_e32 v58, v58
	v_exp_f32_e32 v59, v59
	v_pk_add_f32 v[44:45], v[44:45], 1.0 op_sel_hi:[1,0]
	v_rcp_f32_e32 v44, v44
	v_rcp_f32_e32 v45, v45
	v_pk_fma_f32 v[6:7], v[6:7], v[38:39], v[40:41]
	v_pk_mul_f32 v[46:47], v[6:7], v[42:43]
	v_pk_mul_f32 v[46:47], v[46:47], v[44:45]
	v_cvt_pk_bf16_f32 v48, v46, v47
	global_store_dword v[22:23], v48, off offset:2560
	global_load_dword v97, v[12:13], off offset:-3328 nt
	global_load_dword v98, v[14:15], off offset:-3328 nt
	global_load_dword v99, v[20:21], off offset:-3328 nt
	s_waitcnt vmcnt(52)
	v_lshlrev_b32_e32 v24, 16, v106
	v_and_b32_e32 v25, 0xffff0000, v106
	v_lshlrev_b32_e32 v28, 16, v108
	v_and_b32_e32 v29, 0xffff0000, v108
	v_pk_mul_f32 v[24:25], v[24:25], s[56:57] op_sel_hi:[1,0]
	v_pk_mul_f32 v[30:31], v[28:29], s[58:59] op_sel_hi:[1,0]
	v_lshlrev_b32_e32 v26, 16, v107
	v_and_b32_e32 v27, 0xffff0000, v107
	v_exp_f32_e32 v24, v24
	v_exp_f32_e32 v25, v25
	v_exp_f32_e32 v30, v30
	v_exp_f32_e32 v31, v31
	v_pk_add_f32 v[58:59], v[58:59], 1.0 op_sel_hi:[1,0]
	v_rcp_f32_e32 v58, v58
	v_rcp_f32_e32 v59, v59
	v_pk_fma_f32 v[6:7], v[6:7], v[52:53], v[54:55]
	v_pk_mul_f32 v[60:61], v[6:7], v[56:57]
	v_pk_mul_f32 v[60:61], v[60:61], v[58:59]
	v_cvt_pk_bf16_f32 v62, v60, v61
	global_store_dword v[22:23], v62, off offset:2688
	global_load_dword v100, v[12:13], off offset:-3072 nt
	global_load_dword v101, v[14:15], off offset:-3072 nt
	global_load_dword v102, v[20:21], off offset:-3072 nt
	s_waitcnt vmcnt(52)
	v_lshlrev_b32_e32 v38, 16, v109
	v_and_b32_e32 v39, 0xffff0000, v109
	v_lshlrev_b32_e32 v42, 16, v111
	v_and_b32_e32 v43, 0xffff0000, v111
	v_pk_mul_f32 v[38:39], v[38:39], s[56:57] op_sel_hi:[1,0]
	v_pk_mul_f32 v[44:45], v[42:43], s[58:59] op_sel_hi:[1,0]
	v_lshlrev_b32_e32 v40, 16, v110
	v_and_b32_e32 v41, 0xffff0000, v110
	v_exp_f32_e32 v38, v38
	v_exp_f32_e32 v39, v39
	v_exp_f32_e32 v44, v44
	v_exp_f32_e32 v45, v45
	v_pk_add_f32 v[30:31], v[30:31], 1.0 op_sel_hi:[1,0]
	v_rcp_f32_e32 v30, v30
	v_rcp_f32_e32 v31, v31
	v_pk_fma_f32 v[6:7], v[6:7], v[24:25], v[26:27]
	v_pk_mul_f32 v[32:33], v[6:7], v[28:29]
	v_pk_mul_f32 v[32:33], v[32:33], v[30:31]
	v_cvt_pk_bf16_f32 v34, v32, v33
	global_store_dword v[22:23], v34, off offset:2816
	global_load_dword v103, v[12:13], off offset:-2816 nt
	global_load_dword v104, v[14:15], off offset:-2816 nt
	global_load_dword v105, v[20:21], off offset:-2816 nt
	s_waitcnt vmcnt(52)
	v_lshlrev_b32_e32 v52, 16, v112
	v_and_b32_e32 v53, 0xffff0000, v112
	v_lshlrev_b32_e32 v56, 16, v114
	v_and_b32_e32 v57, 0xffff0000, v114
	v_pk_mul_f32 v[52:53], v[52:53], s[56:57] op_sel_hi:[1,0]
	v_pk_mul_f32 v[58:59], v[56:57], s[58:59] op_sel_hi:[1,0]
	v_lshlrev_b32_e32 v54, 16, v113
	v_and_b32_e32 v55, 0xffff0000, v113
	v_exp_f32_e32 v52, v52
	v_exp_f32_e32 v53, v53
	v_exp_f32_e32 v58, v58
	v_exp_f32_e32 v59, v59
	v_pk_add_f32 v[44:45], v[44:45], 1.0 op_sel_hi:[1,0]
	v_rcp_f32_e32 v44, v44
	v_rcp_f32_e32 v45, v45
	v_pk_fma_f32 v[6:7], v[6:7], v[38:39], v[40:41]
	v_pk_mul_f32 v[46:47], v[6:7], v[42:43]
	v_pk_mul_f32 v[46:47], v[46:47], v[44:45]
	v_cvt_pk_bf16_f32 v48, v46, v47
	global_store_dword v[22:23], v48, off offset:2944
	global_load_dword v106, v[12:13], off offset:-2560 nt
	global_load_dword v107, v[14:15], off offset:-2560 nt
	global_load_dword v108, v[20:21], off offset:-2560 nt
	s_waitcnt vmcnt(52)
	v_lshlrev_b32_e32 v24, 16, v115
	v_and_b32_e32 v25, 0xffff0000, v115
	v_lshlrev_b32_e32 v28, 16, v117
	v_and_b32_e32 v29, 0xffff0000, v117
	v_pk_mul_f32 v[24:25], v[24:25], s[56:57] op_sel_hi:[1,0]
	v_pk_mul_f32 v[30:31], v[28:29], s[58:59] op_sel_hi:[1,0]
	v_lshlrev_b32_e32 v26, 16, v116
	v_and_b32_e32 v27, 0xffff0000, v116
	v_exp_f32_e32 v24, v24
	v_exp_f32_e32 v25, v25
	v_exp_f32_e32 v30, v30
	v_exp_f32_e32 v31, v31
	v_pk_add_f32 v[58:59], v[58:59], 1.0 op_sel_hi:[1,0]
	v_rcp_f32_e32 v58, v58
	v_rcp_f32_e32 v59, v59
	v_pk_fma_f32 v[6:7], v[6:7], v[52:53], v[54:55]
	v_pk_mul_f32 v[60:61], v[6:7], v[56:57]
	v_pk_mul_f32 v[60:61], v[60:61], v[58:59]
	v_cvt_pk_bf16_f32 v62, v60, v61
	global_store_dword v[22:23], v62, off offset:3072
	global_load_dword v109, v[12:13], off offset:-2304 nt
	global_load_dword v110, v[14:15], off offset:-2304 nt
	global_load_dword v111, v[20:21], off offset:-2304 nt
	s_waitcnt vmcnt(52)
	v_lshlrev_b32_e32 v38, 16, v118
	v_and_b32_e32 v39, 0xffff0000, v118
	v_lshlrev_b32_e32 v42, 16, v120
	v_and_b32_e32 v43, 0xffff0000, v120
	v_pk_mul_f32 v[38:39], v[38:39], s[56:57] op_sel_hi:[1,0]
	v_pk_mul_f32 v[44:45], v[42:43], s[58:59] op_sel_hi:[1,0]
	v_lshlrev_b32_e32 v40, 16, v119
	v_and_b32_e32 v41, 0xffff0000, v119
	v_exp_f32_e32 v38, v38
	v_exp_f32_e32 v39, v39
	v_exp_f32_e32 v44, v44
	v_exp_f32_e32 v45, v45
	v_pk_add_f32 v[30:31], v[30:31], 1.0 op_sel_hi:[1,0]
	v_rcp_f32_e32 v30, v30
	v_rcp_f32_e32 v31, v31
	v_pk_fma_f32 v[6:7], v[6:7], v[24:25], v[26:27]
	v_pk_mul_f32 v[32:33], v[6:7], v[28:29]
	v_pk_mul_f32 v[32:33], v[32:33], v[30:31]
	v_cvt_pk_bf16_f32 v34, v32, v33
	global_store_dword v[22:23], v34, off offset:3200
	global_load_dword v112, v[12:13], off offset:-2048 nt
	global_load_dword v113, v[14:15], off offset:-2048 nt
	global_load_dword v114, v[20:21], off offset:-2048 nt
	s_waitcnt vmcnt(52)
	v_lshlrev_b32_e32 v52, 16, v121
	v_and_b32_e32 v53, 0xffff0000, v121
	v_lshlrev_b32_e32 v56, 16, v123
	v_and_b32_e32 v57, 0xffff0000, v123
	v_pk_mul_f32 v[52:53], v[52:53], s[56:57] op_sel_hi:[1,0]
	v_pk_mul_f32 v[58:59], v[56:57], s[58:59] op_sel_hi:[1,0]
	v_lshlrev_b32_e32 v54, 16, v122
	v_and_b32_e32 v55, 0xffff0000, v122
	v_exp_f32_e32 v52, v52
	v_exp_f32_e32 v53, v53
	v_exp_f32_e32 v58, v58
	v_exp_f32_e32 v59, v59
	v_pk_add_f32 v[44:45], v[44:45], 1.0 op_sel_hi:[1,0]
	v_rcp_f32_e32 v44, v44
	v_rcp_f32_e32 v45, v45
	v_pk_fma_f32 v[6:7], v[6:7], v[38:39], v[40:41]
	v_pk_mul_f32 v[46:47], v[6:7], v[42:43]
	v_pk_mul_f32 v[46:47], v[46:47], v[44:45]
	v_cvt_pk_bf16_f32 v48, v46, v47
	global_store_dword v[22:23], v48, off offset:3328
	global_load_dword v115, v[12:13], off offset:-1792 nt
	global_load_dword v116, v[14:15], off offset:-1792 nt
	global_load_dword v117, v[20:21], off offset:-1792 nt
	s_waitcnt vmcnt(52)
	v_lshlrev_b32_e32 v24, 16, v124
	v_and_b32_e32 v25, 0xffff0000, v124
	v_lshlrev_b32_e32 v28, 16, v126
	v_and_b32_e32 v29, 0xffff0000, v126
	v_pk_mul_f32 v[24:25], v[24:25], s[56:57] op_sel_hi:[1,0]
	v_pk_mul_f32 v[30:31], v[28:29], s[58:59] op_sel_hi:[1,0]
	v_lshlrev_b32_e32 v26, 16, v125
	v_and_b32_e32 v27, 0xffff0000, v125
	v_exp_f32_e32 v24, v24
	v_exp_f32_e32 v25, v25
	v_exp_f32_e32 v30, v30
	v_exp_f32_e32 v31, v31
	v_pk_add_f32 v[58:59], v[58:59], 1.0 op_sel_hi:[1,0]
	v_rcp_f32_e32 v58, v58
	v_rcp_f32_e32 v59, v59
	v_pk_fma_f32 v[6:7], v[6:7], v[52:53], v[54:55]
	v_pk_mul_f32 v[60:61], v[6:7], v[56:57]
	v_pk_mul_f32 v[60:61], v[60:61], v[58:59]
	v_cvt_pk_bf16_f32 v62, v60, v61
	global_store_dword v[22:23], v62, off offset:3456
	global_load_dword v118, v[12:13], off offset:-1536 nt
	global_load_dword v119, v[14:15], off offset:-1536 nt
	global_load_dword v120, v[20:21], off offset:-1536 nt
	s_waitcnt vmcnt(52)
	v_lshlrev_b32_e32 v38, 16, v127
	v_and_b32_e32 v39, 0xffff0000, v127
	v_lshlrev_b32_e32 v42, 16, v129
	v_and_b32_e32 v43, 0xffff0000, v129
	v_pk_mul_f32 v[38:39], v[38:39], s[56:57] op_sel_hi:[1,0]
	v_pk_mul_f32 v[44:45], v[42:43], s[58:59] op_sel_hi:[1,0]
	v_lshlrev_b32_e32 v40, 16, v128
	v_and_b32_e32 v41, 0xffff0000, v128
	v_exp_f32_e32 v38, v38
	v_exp_f32_e32 v39, v39
	v_exp_f32_e32 v44, v44
	v_exp_f32_e32 v45, v45
	v_pk_add_f32 v[30:31], v[30:31], 1.0 op_sel_hi:[1,0]
	v_rcp_f32_e32 v30, v30
	v_rcp_f32_e32 v31, v31
	v_pk_fma_f32 v[6:7], v[6:7], v[24:25], v[26:27]
	v_pk_mul_f32 v[32:33], v[6:7], v[28:29]
	v_pk_mul_f32 v[32:33], v[32:33], v[30:31]
	v_cvt_pk_bf16_f32 v34, v32, v33
	global_store_dword v[22:23], v34, off offset:3584
	global_load_dword v121, v[12:13], off offset:-1280 nt
	global_load_dword v122, v[14:15], off offset:-1280 nt
	global_load_dword v123, v[20:21], off offset:-1280 nt
	s_waitcnt vmcnt(52)
	v_lshlrev_b32_e32 v52, 16, v130
	v_and_b32_e32 v53, 0xffff0000, v130
	v_lshlrev_b32_e32 v56, 16, v132
	v_and_b32_e32 v57, 0xffff0000, v132
	v_pk_mul_f32 v[52:53], v[52:53], s[56:57] op_sel_hi:[1,0]
	v_pk_mul_f32 v[58:59], v[56:57], s[58:59] op_sel_hi:[1,0]
	v_lshlrev_b32_e32 v54, 16, v131
	v_and_b32_e32 v55, 0xffff0000, v131
	v_exp_f32_e32 v52, v52
	v_exp_f32_e32 v53, v53
	v_exp_f32_e32 v58, v58
	v_exp_f32_e32 v59, v59
	v_pk_add_f32 v[44:45], v[44:45], 1.0 op_sel_hi:[1,0]
	v_rcp_f32_e32 v44, v44
	v_rcp_f32_e32 v45, v45
	v_pk_fma_f32 v[6:7], v[6:7], v[38:39], v[40:41]
	v_pk_mul_f32 v[46:47], v[6:7], v[42:43]
	v_pk_mul_f32 v[46:47], v[46:47], v[44:45]
	v_cvt_pk_bf16_f32 v48, v46, v47
	global_store_dword v[22:23], v48, off offset:3712
	global_load_dword v124, v[12:13], off offset:-1024 nt
	global_load_dword v125, v[14:15], off offset:-1024 nt
	global_load_dword v126, v[20:21], off offset:-1024 nt
	s_waitcnt vmcnt(52)
	v_lshlrev_b32_e32 v24, 16, v133
	v_and_b32_e32 v25, 0xffff0000, v133
	v_lshlrev_b32_e32 v28, 16, v135
	v_and_b32_e32 v29, 0xffff0000, v135
	v_pk_mul_f32 v[24:25], v[24:25], s[56:57] op_sel_hi:[1,0]
	v_pk_mul_f32 v[30:31], v[28:29], s[58:59] op_sel_hi:[1,0]
	v_lshlrev_b32_e32 v26, 16, v134
	v_and_b32_e32 v27, 0xffff0000, v134
	v_exp_f32_e32 v24, v24
	v_exp_f32_e32 v25, v25
	v_exp_f32_e32 v30, v30
	v_exp_f32_e32 v31, v31
	v_pk_add_f32 v[58:59], v[58:59], 1.0 op_sel_hi:[1,0]
	v_rcp_f32_e32 v58, v58
	v_rcp_f32_e32 v59, v59
	v_pk_fma_f32 v[6:7], v[6:7], v[52:53], v[54:55]
	v_pk_mul_f32 v[60:61], v[6:7], v[56:57]
	v_pk_mul_f32 v[60:61], v[60:61], v[58:59]
	v_cvt_pk_bf16_f32 v62, v60, v61
	global_store_dword v[22:23], v62, off offset:3840
	global_load_dword v127, v[12:13], off offset:-768 nt
	global_load_dword v128, v[14:15], off offset:-768 nt
	global_load_dword v129, v[20:21], off offset:-768 nt
	s_waitcnt vmcnt(52)
	v_lshlrev_b32_e32 v38, 16, v88
	v_and_b32_e32 v39, 0xffff0000, v88
	v_lshlrev_b32_e32 v42, 16, v90
	v_and_b32_e32 v43, 0xffff0000, v90
	v_pk_mul_f32 v[38:39], v[38:39], s[56:57] op_sel_hi:[1,0]
	v_pk_mul_f32 v[44:45], v[42:43], s[58:59] op_sel_hi:[1,0]
	v_lshlrev_b32_e32 v40, 16, v89
	v_and_b32_e32 v41, 0xffff0000, v89
	v_exp_f32_e32 v38, v38
	v_exp_f32_e32 v39, v39
	v_exp_f32_e32 v44, v44
	v_exp_f32_e32 v45, v45
	v_pk_add_f32 v[30:31], v[30:31], 1.0 op_sel_hi:[1,0]
	v_rcp_f32_e32 v30, v30
	v_rcp_f32_e32 v31, v31
	v_pk_fma_f32 v[6:7], v[6:7], v[24:25], v[26:27]
	v_pk_mul_f32 v[32:33], v[6:7], v[28:29]
	v_pk_mul_f32 v[32:33], v[32:33], v[30:31]
	v_cvt_pk_bf16_f32 v34, v32, v33
	global_store_dword v[22:23], v34, off offset:3968
	global_load_dword v130, v[12:13], off offset:-512 nt
	global_load_dword v131, v[14:15], off offset:-512 nt
	global_load_dword v132, v[20:21], off offset:-512 nt
	s_waitcnt vmcnt(52)
	v_lshlrev_b32_e32 v52, 16, v91
	v_and_b32_e32 v53, 0xffff0000, v91
	v_lshlrev_b32_e32 v56, 16, v93
	v_and_b32_e32 v57, 0xffff0000, v93
	v_pk_mul_f32 v[52:53], v[52:53], s[56:57] op_sel_hi:[1,0]
	v_pk_mul_f32 v[58:59], v[56:57], s[58:59] op_sel_hi:[1,0]
	v_lshlrev_b32_e32 v54, 16, v92
	v_and_b32_e32 v55, 0xffff0000, v92
	v_exp_f32_e32 v52, v52
	v_exp_f32_e32 v53, v53
	v_exp_f32_e32 v58, v58
	v_exp_f32_e32 v59, v59
	v_pk_add_f32 v[44:45], v[44:45], 1.0 op_sel_hi:[1,0]
	v_rcp_f32_e32 v44, v44
	v_rcp_f32_e32 v45, v45
	v_pk_fma_f32 v[6:7], v[6:7], v[38:39], v[40:41]
	v_pk_mul_f32 v[46:47], v[6:7], v[42:43]
	v_pk_mul_f32 v[46:47], v[46:47], v[44:45]
	v_cvt_pk_bf16_f32 v48, v46, v47
	v_lshl_add_u64 v[22:23], v[22:23], 0, s[60:61]
	v_lshl_add_u64 v[22:23], v[22:23], 0, s[60:61]
	global_store_dword v[22:23], v48, off offset:-4096
	global_load_dword v133, v[12:13], off offset:-256 nt
	global_load_dword v134, v[14:15], off offset:-256 nt
	global_load_dword v135, v[20:21], off offset:-256 nt
	s_waitcnt vmcnt(52)
	v_lshlrev_b32_e32 v24, 16, v94
	v_and_b32_e32 v25, 0xffff0000, v94
	v_lshlrev_b32_e32 v28, 16, v96
	v_and_b32_e32 v29, 0xffff0000, v96
	v_pk_mul_f32 v[24:25], v[24:25], s[56:57] op_sel_hi:[1,0]
	v_pk_mul_f32 v[30:31], v[28:29], s[58:59] op_sel_hi:[1,0]
	v_lshlrev_b32_e32 v26, 16, v95
	v_and_b32_e32 v27, 0xffff0000, v95
	v_exp_f32_e32 v24, v24
	v_exp_f32_e32 v25, v25
	v_exp_f32_e32 v30, v30
	v_exp_f32_e32 v31, v31
	v_pk_add_f32 v[58:59], v[58:59], 1.0 op_sel_hi:[1,0]
	v_rcp_f32_e32 v58, v58
	v_rcp_f32_e32 v59, v59
	v_pk_fma_f32 v[6:7], v[6:7], v[52:53], v[54:55]
	v_pk_mul_f32 v[60:61], v[6:7], v[56:57]
	v_pk_mul_f32 v[60:61], v[60:61], v[58:59]
	v_cvt_pk_bf16_f32 v62, v60, v61
	global_store_dword v[22:23], v62, off offset:-3968
	global_load_dword v88, v[12:13], off nt
	global_load_dword v89, v[14:15], off nt
	global_load_dword v90, v[20:21], off nt
	s_waitcnt vmcnt(52)
	v_lshlrev_b32_e32 v38, 16, v97
	v_and_b32_e32 v39, 0xffff0000, v97
	v_lshlrev_b32_e32 v42, 16, v99
	v_and_b32_e32 v43, 0xffff0000, v99
	v_pk_mul_f32 v[38:39], v[38:39], s[56:57] op_sel_hi:[1,0]
	v_pk_mul_f32 v[44:45], v[42:43], s[58:59] op_sel_hi:[1,0]
	v_lshlrev_b32_e32 v40, 16, v98
	v_and_b32_e32 v41, 0xffff0000, v98
	v_exp_f32_e32 v38, v38
	v_exp_f32_e32 v39, v39
	v_exp_f32_e32 v44, v44
	v_exp_f32_e32 v45, v45
	v_pk_add_f32 v[30:31], v[30:31], 1.0 op_sel_hi:[1,0]
	v_rcp_f32_e32 v30, v30
	v_rcp_f32_e32 v31, v31
	v_pk_fma_f32 v[6:7], v[6:7], v[24:25], v[26:27]
	v_pk_mul_f32 v[32:33], v[6:7], v[28:29]
	v_pk_mul_f32 v[32:33], v[32:33], v[30:31]
	v_cvt_pk_bf16_f32 v34, v32, v33
	global_store_dword v[22:23], v34, off offset:-3840
	global_load_dword v91, v[12:13], off offset:256 nt
	global_load_dword v92, v[14:15], off offset:256 nt
	global_load_dword v93, v[20:21], off offset:256 nt
	s_waitcnt vmcnt(52)
	v_lshlrev_b32_e32 v52, 16, v100
	v_and_b32_e32 v53, 0xffff0000, v100
	v_lshlrev_b32_e32 v56, 16, v102
	v_and_b32_e32 v57, 0xffff0000, v102
	v_pk_mul_f32 v[52:53], v[52:53], s[56:57] op_sel_hi:[1,0]
	v_pk_mul_f32 v[58:59], v[56:57], s[58:59] op_sel_hi:[1,0]
	v_lshlrev_b32_e32 v54, 16, v101
	v_and_b32_e32 v55, 0xffff0000, v101
	v_exp_f32_e32 v52, v52
	v_exp_f32_e32 v53, v53
	v_exp_f32_e32 v58, v58
	v_exp_f32_e32 v59, v59
	v_pk_add_f32 v[44:45], v[44:45], 1.0 op_sel_hi:[1,0]
	v_rcp_f32_e32 v44, v44
	v_rcp_f32_e32 v45, v45
	v_pk_fma_f32 v[6:7], v[6:7], v[38:39], v[40:41]
	v_pk_mul_f32 v[46:47], v[6:7], v[42:43]
	v_pk_mul_f32 v[46:47], v[46:47], v[44:45]
	v_cvt_pk_bf16_f32 v48, v46, v47
	global_store_dword v[22:23], v48, off offset:-3712
	global_load_dword v94, v[12:13], off offset:512 nt
	global_load_dword v95, v[14:15], off offset:512 nt
	global_load_dword v96, v[20:21], off offset:512 nt
	s_waitcnt vmcnt(52)
	v_lshlrev_b32_e32 v24, 16, v103
	v_and_b32_e32 v25, 0xffff0000, v103
	v_lshlrev_b32_e32 v28, 16, v105
	v_and_b32_e32 v29, 0xffff0000, v105
	v_pk_mul_f32 v[24:25], v[24:25], s[56:57] op_sel_hi:[1,0]
	v_pk_mul_f32 v[30:31], v[28:29], s[58:59] op_sel_hi:[1,0]
	v_lshlrev_b32_e32 v26, 16, v104
	v_and_b32_e32 v27, 0xffff0000, v104
	v_exp_f32_e32 v24, v24
	v_exp_f32_e32 v25, v25
	v_exp_f32_e32 v30, v30
	v_exp_f32_e32 v31, v31
	v_pk_add_f32 v[58:59], v[58:59], 1.0 op_sel_hi:[1,0]
	v_rcp_f32_e32 v58, v58
	v_rcp_f32_e32 v59, v59
	v_pk_fma_f32 v[6:7], v[6:7], v[52:53], v[54:55]
	v_pk_mul_f32 v[60:61], v[6:7], v[56:57]
	v_pk_mul_f32 v[60:61], v[60:61], v[58:59]
	v_cvt_pk_bf16_f32 v62, v60, v61
	global_store_dword v[22:23], v62, off offset:-3584
	global_load_dword v97, v[12:13], off offset:768 nt
	global_load_dword v98, v[14:15], off offset:768 nt
	global_load_dword v99, v[20:21], off offset:768 nt
	s_waitcnt vmcnt(52)
	v_lshlrev_b32_e32 v38, 16, v106
	v_and_b32_e32 v39, 0xffff0000, v106
	v_lshlrev_b32_e32 v42, 16, v108
	v_and_b32_e32 v43, 0xffff0000, v108
	v_pk_mul_f32 v[38:39], v[38:39], s[56:57] op_sel_hi:[1,0]
	v_pk_mul_f32 v[44:45], v[42:43], s[58:59] op_sel_hi:[1,0]
	v_lshlrev_b32_e32 v40, 16, v107
	v_and_b32_e32 v41, 0xffff0000, v107
	v_exp_f32_e32 v38, v38
	v_exp_f32_e32 v39, v39
	v_exp_f32_e32 v44, v44
	v_exp_f32_e32 v45, v45
	v_pk_add_f32 v[30:31], v[30:31], 1.0 op_sel_hi:[1,0]
	v_rcp_f32_e32 v30, v30
	v_rcp_f32_e32 v31, v31
	v_pk_fma_f32 v[6:7], v[6:7], v[24:25], v[26:27]
	v_pk_mul_f32 v[32:33], v[6:7], v[28:29]
	v_pk_mul_f32 v[32:33], v[32:33], v[30:31]
	v_cvt_pk_bf16_f32 v34, v32, v33
	global_store_dword v[22:23], v34, off offset:-3456
	global_load_dword v100, v[12:13], off offset:1024 nt
	global_load_dword v101, v[14:15], off offset:1024 nt
	global_load_dword v102, v[20:21], off offset:1024 nt
	s_waitcnt vmcnt(52)
	v_lshlrev_b32_e32 v52, 16, v109
	v_and_b32_e32 v53, 0xffff0000, v109
	v_lshlrev_b32_e32 v56, 16, v111
	v_and_b32_e32 v57, 0xffff0000, v111
	v_pk_mul_f32 v[52:53], v[52:53], s[56:57] op_sel_hi:[1,0]
	v_pk_mul_f32 v[58:59], v[56:57], s[58:59] op_sel_hi:[1,0]
	v_lshlrev_b32_e32 v54, 16, v110
	v_and_b32_e32 v55, 0xffff0000, v110
	v_exp_f32_e32 v52, v52
	v_exp_f32_e32 v53, v53
	v_exp_f32_e32 v58, v58
	v_exp_f32_e32 v59, v59
	v_pk_add_f32 v[44:45], v[44:45], 1.0 op_sel_hi:[1,0]
	v_rcp_f32_e32 v44, v44
	v_rcp_f32_e32 v45, v45
	v_pk_fma_f32 v[6:7], v[6:7], v[38:39], v[40:41]
	v_pk_mul_f32 v[46:47], v[6:7], v[42:43]
	v_pk_mul_f32 v[46:47], v[46:47], v[44:45]
	v_cvt_pk_bf16_f32 v48, v46, v47
	global_store_dword v[22:23], v48, off offset:-3328
	global_load_dword v103, v[12:13], off offset:1280 nt
	global_load_dword v104, v[14:15], off offset:1280 nt
	global_load_dword v105, v[20:21], off offset:1280 nt
	s_waitcnt vmcnt(52)
	v_lshlrev_b32_e32 v24, 16, v112
	v_and_b32_e32 v25, 0xffff0000, v112
	v_lshlrev_b32_e32 v28, 16, v114
	v_and_b32_e32 v29, 0xffff0000, v114
	v_pk_mul_f32 v[24:25], v[24:25], s[56:57] op_sel_hi:[1,0]
	v_pk_mul_f32 v[30:31], v[28:29], s[58:59] op_sel_hi:[1,0]
	v_lshlrev_b32_e32 v26, 16, v113
	v_and_b32_e32 v27, 0xffff0000, v113
	v_exp_f32_e32 v24, v24
	v_exp_f32_e32 v25, v25
	v_exp_f32_e32 v30, v30
	v_exp_f32_e32 v31, v31
	v_pk_add_f32 v[58:59], v[58:59], 1.0 op_sel_hi:[1,0]
	v_rcp_f32_e32 v58, v58
	v_rcp_f32_e32 v59, v59
	v_pk_fma_f32 v[6:7], v[6:7], v[52:53], v[54:55]
	v_pk_mul_f32 v[60:61], v[6:7], v[56:57]
	v_pk_mul_f32 v[60:61], v[60:61], v[58:59]
	v_cvt_pk_bf16_f32 v62, v60, v61
	global_store_dword v[22:23], v62, off offset:-3200
	global_load_dword v106, v[12:13], off offset:1536 nt
	global_load_dword v107, v[14:15], off offset:1536 nt
	global_load_dword v108, v[20:21], off offset:1536 nt
	s_waitcnt vmcnt(52)
	v_lshlrev_b32_e32 v38, 16, v115
	v_and_b32_e32 v39, 0xffff0000, v115
	v_lshlrev_b32_e32 v42, 16, v117
	v_and_b32_e32 v43, 0xffff0000, v117
	v_pk_mul_f32 v[38:39], v[38:39], s[56:57] op_sel_hi:[1,0]
	v_pk_mul_f32 v[44:45], v[42:43], s[58:59] op_sel_hi:[1,0]
	v_lshlrev_b32_e32 v40, 16, v116
	v_and_b32_e32 v41, 0xffff0000, v116
	v_exp_f32_e32 v38, v38
	v_exp_f32_e32 v39, v39
	v_exp_f32_e32 v44, v44
	v_exp_f32_e32 v45, v45
	v_pk_add_f32 v[30:31], v[30:31], 1.0 op_sel_hi:[1,0]
	v_rcp_f32_e32 v30, v30
	v_rcp_f32_e32 v31, v31
	v_pk_fma_f32 v[6:7], v[6:7], v[24:25], v[26:27]
	v_pk_mul_f32 v[32:33], v[6:7], v[28:29]
	v_pk_mul_f32 v[32:33], v[32:33], v[30:31]
	v_cvt_pk_bf16_f32 v34, v32, v33
	global_store_dword v[22:23], v34, off offset:-3072
	global_load_dword v109, v[12:13], off offset:1792 nt
	global_load_dword v110, v[14:15], off offset:1792 nt
	global_load_dword v111, v[20:21], off offset:1792 nt
	s_waitcnt vmcnt(52)
	v_lshlrev_b32_e32 v52, 16, v118
	v_and_b32_e32 v53, 0xffff0000, v118
	v_lshlrev_b32_e32 v56, 16, v120
	v_and_b32_e32 v57, 0xffff0000, v120
	v_pk_mul_f32 v[52:53], v[52:53], s[56:57] op_sel_hi:[1,0]
	v_pk_mul_f32 v[58:59], v[56:57], s[58:59] op_sel_hi:[1,0]
	v_lshlrev_b32_e32 v54, 16, v119
	v_and_b32_e32 v55, 0xffff0000, v119
	v_exp_f32_e32 v52, v52
	v_exp_f32_e32 v53, v53
	v_exp_f32_e32 v58, v58
	v_exp_f32_e32 v59, v59
	v_pk_add_f32 v[44:45], v[44:45], 1.0 op_sel_hi:[1,0]
	v_rcp_f32_e32 v44, v44
	v_rcp_f32_e32 v45, v45
	v_pk_fma_f32 v[6:7], v[6:7], v[38:39], v[40:41]
	v_pk_mul_f32 v[46:47], v[6:7], v[42:43]
	v_pk_mul_f32 v[46:47], v[46:47], v[44:45]
	v_cvt_pk_bf16_f32 v48, v46, v47
	global_store_dword v[22:23], v48, off offset:-2944
	global_load_dword v112, v[12:13], off offset:2048 nt
	global_load_dword v113, v[14:15], off offset:2048 nt
	global_load_dword v114, v[20:21], off offset:2048 nt
	s_waitcnt vmcnt(52)
	v_lshlrev_b32_e32 v24, 16, v121
	v_and_b32_e32 v25, 0xffff0000, v121
	v_lshlrev_b32_e32 v28, 16, v123
	v_and_b32_e32 v29, 0xffff0000, v123
	v_pk_mul_f32 v[24:25], v[24:25], s[56:57] op_sel_hi:[1,0]
	v_pk_mul_f32 v[30:31], v[28:29], s[58:59] op_sel_hi:[1,0]
	v_lshlrev_b32_e32 v26, 16, v122
	v_and_b32_e32 v27, 0xffff0000, v122
	v_exp_f32_e32 v24, v24
	v_exp_f32_e32 v25, v25
	v_exp_f32_e32 v30, v30
	v_exp_f32_e32 v31, v31
	v_pk_add_f32 v[58:59], v[58:59], 1.0 op_sel_hi:[1,0]
	v_rcp_f32_e32 v58, v58
	v_rcp_f32_e32 v59, v59
	v_pk_fma_f32 v[6:7], v[6:7], v[52:53], v[54:55]
	v_pk_mul_f32 v[60:61], v[6:7], v[56:57]
	v_pk_mul_f32 v[60:61], v[60:61], v[58:59]
	v_cvt_pk_bf16_f32 v62, v60, v61
	global_store_dword v[22:23], v62, off offset:-2816
	global_load_dword v115, v[12:13], off offset:2304 nt
	global_load_dword v116, v[14:15], off offset:2304 nt
	global_load_dword v117, v[20:21], off offset:2304 nt
	s_waitcnt vmcnt(52)
	v_lshlrev_b32_e32 v38, 16, v124
	v_and_b32_e32 v39, 0xffff0000, v124
	v_lshlrev_b32_e32 v42, 16, v126
	v_and_b32_e32 v43, 0xffff0000, v126
	v_pk_mul_f32 v[38:39], v[38:39], s[56:57] op_sel_hi:[1,0]
	v_pk_mul_f32 v[44:45], v[42:43], s[58:59] op_sel_hi:[1,0]
	v_lshlrev_b32_e32 v40, 16, v125
	v_and_b32_e32 v41, 0xffff0000, v125
	v_exp_f32_e32 v38, v38
	v_exp_f32_e32 v39, v39
	v_exp_f32_e32 v44, v44
	v_exp_f32_e32 v45, v45
	v_pk_add_f32 v[30:31], v[30:31], 1.0 op_sel_hi:[1,0]
	v_rcp_f32_e32 v30, v30
	v_rcp_f32_e32 v31, v31
	v_pk_fma_f32 v[6:7], v[6:7], v[24:25], v[26:27]
	v_pk_mul_f32 v[32:33], v[6:7], v[28:29]
	v_pk_mul_f32 v[32:33], v[32:33], v[30:31]
	v_cvt_pk_bf16_f32 v34, v32, v33
	global_store_dword v[22:23], v34, off offset:-2688
	global_load_dword v118, v[12:13], off offset:2560 nt
	global_load_dword v119, v[14:15], off offset:2560 nt
	global_load_dword v120, v[20:21], off offset:2560 nt
	s_waitcnt vmcnt(52)
	v_lshlrev_b32_e32 v52, 16, v127
	v_and_b32_e32 v53, 0xffff0000, v127
	v_lshlrev_b32_e32 v56, 16, v129
	v_and_b32_e32 v57, 0xffff0000, v129
	v_pk_mul_f32 v[52:53], v[52:53], s[56:57] op_sel_hi:[1,0]
	v_pk_mul_f32 v[58:59], v[56:57], s[58:59] op_sel_hi:[1,0]
	v_lshlrev_b32_e32 v54, 16, v128
	v_and_b32_e32 v55, 0xffff0000, v128
	v_exp_f32_e32 v52, v52
	v_exp_f32_e32 v53, v53
	v_exp_f32_e32 v58, v58
	v_exp_f32_e32 v59, v59
	v_pk_add_f32 v[44:45], v[44:45], 1.0 op_sel_hi:[1,0]
	v_rcp_f32_e32 v44, v44
	v_rcp_f32_e32 v45, v45
	v_pk_fma_f32 v[6:7], v[6:7], v[38:39], v[40:41]
	v_pk_mul_f32 v[46:47], v[6:7], v[42:43]
	v_pk_mul_f32 v[46:47], v[46:47], v[44:45]
	v_cvt_pk_bf16_f32 v48, v46, v47
	global_store_dword v[22:23], v48, off offset:-2560
	global_load_dword v121, v[12:13], off offset:2816 nt
	global_load_dword v122, v[14:15], off offset:2816 nt
	global_load_dword v123, v[20:21], off offset:2816 nt
	s_waitcnt vmcnt(52)
	v_lshlrev_b32_e32 v24, 16, v130
	v_and_b32_e32 v25, 0xffff0000, v130
	v_lshlrev_b32_e32 v28, 16, v132
	v_and_b32_e32 v29, 0xffff0000, v132
	v_pk_mul_f32 v[24:25], v[24:25], s[56:57] op_sel_hi:[1,0]
	v_pk_mul_f32 v[30:31], v[28:29], s[58:59] op_sel_hi:[1,0]
	v_lshlrev_b32_e32 v26, 16, v131
	v_and_b32_e32 v27, 0xffff0000, v131
	v_exp_f32_e32 v24, v24
	v_exp_f32_e32 v25, v25
	v_exp_f32_e32 v30, v30
	v_exp_f32_e32 v31, v31
	v_pk_add_f32 v[58:59], v[58:59], 1.0 op_sel_hi:[1,0]
	v_rcp_f32_e32 v58, v58
	v_rcp_f32_e32 v59, v59
	v_pk_fma_f32 v[6:7], v[6:7], v[52:53], v[54:55]
	v_pk_mul_f32 v[60:61], v[6:7], v[56:57]
	v_pk_mul_f32 v[60:61], v[60:61], v[58:59]
	v_cvt_pk_bf16_f32 v62, v60, v61
	global_store_dword v[22:23], v62, off offset:-2432
	global_load_dword v124, v[12:13], off offset:3072 nt
	global_load_dword v125, v[14:15], off offset:3072 nt
	global_load_dword v126, v[20:21], off offset:3072 nt
	s_waitcnt vmcnt(52)
	v_lshlrev_b32_e32 v38, 16, v133
	v_and_b32_e32 v39, 0xffff0000, v133
	v_lshlrev_b32_e32 v42, 16, v135
	v_and_b32_e32 v43, 0xffff0000, v135
	v_pk_mul_f32 v[38:39], v[38:39], s[56:57] op_sel_hi:[1,0]
	v_pk_mul_f32 v[44:45], v[42:43], s[58:59] op_sel_hi:[1,0]
	v_lshlrev_b32_e32 v40, 16, v134
	v_and_b32_e32 v41, 0xffff0000, v134
	v_exp_f32_e32 v38, v38
	v_exp_f32_e32 v39, v39
	v_exp_f32_e32 v44, v44
	v_exp_f32_e32 v45, v45
	v_pk_add_f32 v[30:31], v[30:31], 1.0 op_sel_hi:[1,0]
	v_rcp_f32_e32 v30, v30
	v_rcp_f32_e32 v31, v31
	v_pk_fma_f32 v[6:7], v[6:7], v[24:25], v[26:27]
	v_pk_mul_f32 v[32:33], v[6:7], v[28:29]
	v_pk_mul_f32 v[32:33], v[32:33], v[30:31]
	v_cvt_pk_bf16_f32 v34, v32, v33
	global_store_dword v[22:23], v34, off offset:-2304
	global_load_dword v127, v[12:13], off offset:3328 nt
	global_load_dword v128, v[14:15], off offset:3328 nt
	global_load_dword v129, v[20:21], off offset:3328 nt
	s_waitcnt vmcnt(52)
	v_lshlrev_b32_e32 v52, 16, v88
	v_and_b32_e32 v53, 0xffff0000, v88
	v_lshlrev_b32_e32 v56, 16, v90
	v_and_b32_e32 v57, 0xffff0000, v90
	v_pk_mul_f32 v[52:53], v[52:53], s[56:57] op_sel_hi:[1,0]
	v_pk_mul_f32 v[58:59], v[56:57], s[58:59] op_sel_hi:[1,0]
	v_lshlrev_b32_e32 v54, 16, v89
	v_and_b32_e32 v55, 0xffff0000, v89
	v_exp_f32_e32 v52, v52
	v_exp_f32_e32 v53, v53
	v_exp_f32_e32 v58, v58
	v_exp_f32_e32 v59, v59
	v_pk_add_f32 v[44:45], v[44:45], 1.0 op_sel_hi:[1,0]
	v_rcp_f32_e32 v44, v44
	v_rcp_f32_e32 v45, v45
	v_pk_fma_f32 v[6:7], v[6:7], v[38:39], v[40:41]
	v_pk_mul_f32 v[46:47], v[6:7], v[42:43]
	v_pk_mul_f32 v[46:47], v[46:47], v[44:45]
	v_cvt_pk_bf16_f32 v48, v46, v47
	global_store_dword v[22:23], v48, off offset:-2176
	global_load_dword v130, v[12:13], off offset:3584 nt
	global_load_dword v131, v[14:15], off offset:3584 nt
	global_load_dword v132, v[20:21], off offset:3584 nt
	s_waitcnt vmcnt(52)
	v_lshlrev_b32_e32 v24, 16, v91
	v_and_b32_e32 v25, 0xffff0000, v91
	v_lshlrev_b32_e32 v28, 16, v93
	v_and_b32_e32 v29, 0xffff0000, v93
	v_pk_mul_f32 v[24:25], v[24:25], s[56:57] op_sel_hi:[1,0]
	v_pk_mul_f32 v[30:31], v[28:29], s[58:59] op_sel_hi:[1,0]
	v_lshlrev_b32_e32 v26, 16, v92
	v_and_b32_e32 v27, 0xffff0000, v92
	v_exp_f32_e32 v24, v24
	v_exp_f32_e32 v25, v25
	v_exp_f32_e32 v30, v30
	v_exp_f32_e32 v31, v31
	v_pk_add_f32 v[58:59], v[58:59], 1.0 op_sel_hi:[1,0]
	v_rcp_f32_e32 v58, v58
	v_rcp_f32_e32 v59, v59
	v_pk_fma_f32 v[6:7], v[6:7], v[52:53], v[54:55]
	v_pk_mul_f32 v[60:61], v[6:7], v[56:57]
	v_pk_mul_f32 v[60:61], v[60:61], v[58:59]
	v_cvt_pk_bf16_f32 v62, v60, v61
	global_store_dword v[22:23], v62, off offset:-2048
	global_load_dword v133, v[12:13], off offset:3840 nt
	global_load_dword v134, v[14:15], off offset:3840 nt
	global_load_dword v135, v[20:21], off offset:3840 nt
	s_waitcnt vmcnt(52)
	v_lshlrev_b32_e32 v38, 16, v94
	v_and_b32_e32 v39, 0xffff0000, v94
	v_lshlrev_b32_e32 v42, 16, v96
	v_and_b32_e32 v43, 0xffff0000, v96
	v_pk_mul_f32 v[38:39], v[38:39], s[56:57] op_sel_hi:[1,0]
	v_pk_mul_f32 v[44:45], v[42:43], s[58:59] op_sel_hi:[1,0]
	v_lshlrev_b32_e32 v40, 16, v95
	v_and_b32_e32 v41, 0xffff0000, v95
	v_exp_f32_e32 v38, v38
	v_exp_f32_e32 v39, v39
	v_exp_f32_e32 v44, v44
	v_exp_f32_e32 v45, v45
	v_pk_add_f32 v[30:31], v[30:31], 1.0 op_sel_hi:[1,0]
	v_rcp_f32_e32 v30, v30
	v_rcp_f32_e32 v31, v31
	v_pk_fma_f32 v[6:7], v[6:7], v[24:25], v[26:27]
	v_pk_mul_f32 v[32:33], v[6:7], v[28:29]
	v_pk_mul_f32 v[32:33], v[32:33], v[30:31]
	v_cvt_pk_bf16_f32 v34, v32, v33
	global_store_dword v[22:23], v34, off offset:-1920
	v_lshl_add_u64 v[12:13], v[12:13], 0, s[60:61]
	v_lshl_add_u64 v[12:13], v[12:13], 0, s[60:61]
	v_lshl_add_u64 v[14:15], v[14:15], 0, s[60:61]
	v_lshl_add_u64 v[14:15], v[14:15], 0, s[60:61]
	v_lshl_add_u64 v[20:21], v[20:21], 0, s[60:61]
	v_lshl_add_u64 v[20:21], v[20:21], 0, s[60:61]
	global_load_dword v88, v[12:13], off offset:-4096 nt
	global_load_dword v89, v[14:15], off offset:-4096 nt
	global_load_dword v90, v[20:21], off offset:-4096 nt
	s_waitcnt vmcnt(52)
	v_lshlrev_b32_e32 v52, 16, v97
	v_and_b32_e32 v53, 0xffff0000, v97
	v_lshlrev_b32_e32 v56, 16, v99
	v_and_b32_e32 v57, 0xffff0000, v99
	v_pk_mul_f32 v[52:53], v[52:53], s[56:57] op_sel_hi:[1,0]
	v_pk_mul_f32 v[58:59], v[56:57], s[58:59] op_sel_hi:[1,0]
	v_lshlrev_b32_e32 v54, 16, v98
	v_and_b32_e32 v55, 0xffff0000, v98
	v_exp_f32_e32 v52, v52
	v_exp_f32_e32 v53, v53
	v_exp_f32_e32 v58, v58
	v_exp_f32_e32 v59, v59
	v_pk_add_f32 v[44:45], v[44:45], 1.0 op_sel_hi:[1,0]
	v_rcp_f32_e32 v44, v44
	v_rcp_f32_e32 v45, v45
	v_pk_fma_f32 v[6:7], v[6:7], v[38:39], v[40:41]
	v_pk_mul_f32 v[46:47], v[6:7], v[42:43]
	v_pk_mul_f32 v[46:47], v[46:47], v[44:45]
	v_cvt_pk_bf16_f32 v48, v46, v47
	global_store_dword v[22:23], v48, off offset:-1792
	global_load_dword v91, v[12:13], off offset:-3840 nt
	global_load_dword v92, v[14:15], off offset:-3840 nt
	global_load_dword v93, v[20:21], off offset:-3840 nt
	s_waitcnt vmcnt(52)
	v_lshlrev_b32_e32 v24, 16, v100
	v_and_b32_e32 v25, 0xffff0000, v100
	v_lshlrev_b32_e32 v28, 16, v102
	v_and_b32_e32 v29, 0xffff0000, v102
	v_pk_mul_f32 v[24:25], v[24:25], s[56:57] op_sel_hi:[1,0]
	v_pk_mul_f32 v[30:31], v[28:29], s[58:59] op_sel_hi:[1,0]
	v_lshlrev_b32_e32 v26, 16, v101
	v_and_b32_e32 v27, 0xffff0000, v101
	v_exp_f32_e32 v24, v24
	v_exp_f32_e32 v25, v25
	v_exp_f32_e32 v30, v30
	v_exp_f32_e32 v31, v31
	v_pk_add_f32 v[58:59], v[58:59], 1.0 op_sel_hi:[1,0]
	v_rcp_f32_e32 v58, v58
	v_rcp_f32_e32 v59, v59
	v_pk_fma_f32 v[6:7], v[6:7], v[52:53], v[54:55]
	v_pk_mul_f32 v[60:61], v[6:7], v[56:57]
	v_pk_mul_f32 v[60:61], v[60:61], v[58:59]
	v_cvt_pk_bf16_f32 v62, v60, v61
	global_store_dword v[22:23], v62, off offset:-1664
	global_load_dword v94, v[12:13], off offset:-3584 nt
	global_load_dword v95, v[14:15], off offset:-3584 nt
	global_load_dword v96, v[20:21], off offset:-3584 nt
	s_waitcnt vmcnt(52)
	v_lshlrev_b32_e32 v38, 16, v103
	v_and_b32_e32 v39, 0xffff0000, v103
	v_lshlrev_b32_e32 v42, 16, v105
	v_and_b32_e32 v43, 0xffff0000, v105
	v_pk_mul_f32 v[38:39], v[38:39], s[56:57] op_sel_hi:[1,0]
	v_pk_mul_f32 v[44:45], v[42:43], s[58:59] op_sel_hi:[1,0]
	v_lshlrev_b32_e32 v40, 16, v104
	v_and_b32_e32 v41, 0xffff0000, v104
	v_exp_f32_e32 v38, v38
	v_exp_f32_e32 v39, v39
	v_exp_f32_e32 v44, v44
	v_exp_f32_e32 v45, v45
	v_pk_add_f32 v[30:31], v[30:31], 1.0 op_sel_hi:[1,0]
	v_rcp_f32_e32 v30, v30
	v_rcp_f32_e32 v31, v31
	v_pk_fma_f32 v[6:7], v[6:7], v[24:25], v[26:27]
	v_pk_mul_f32 v[32:33], v[6:7], v[28:29]
	v_pk_mul_f32 v[32:33], v[32:33], v[30:31]
	v_cvt_pk_bf16_f32 v34, v32, v33
	global_store_dword v[22:23], v34, off offset:-1536
	global_load_dword v97, v[12:13], off offset:-3328 nt
	global_load_dword v98, v[14:15], off offset:-3328 nt
	global_load_dword v99, v[20:21], off offset:-3328 nt
	s_waitcnt vmcnt(52)
	v_lshlrev_b32_e32 v52, 16, v106
	v_and_b32_e32 v53, 0xffff0000, v106
	v_lshlrev_b32_e32 v56, 16, v108
	v_and_b32_e32 v57, 0xffff0000, v108
	v_pk_mul_f32 v[52:53], v[52:53], s[56:57] op_sel_hi:[1,0]
	v_pk_mul_f32 v[58:59], v[56:57], s[58:59] op_sel_hi:[1,0]
	v_lshlrev_b32_e32 v54, 16, v107
	v_and_b32_e32 v55, 0xffff0000, v107
	v_exp_f32_e32 v52, v52
	v_exp_f32_e32 v53, v53
	v_exp_f32_e32 v58, v58
	v_exp_f32_e32 v59, v59
	v_pk_add_f32 v[44:45], v[44:45], 1.0 op_sel_hi:[1,0]
	v_rcp_f32_e32 v44, v44
	v_rcp_f32_e32 v45, v45
	v_pk_fma_f32 v[6:7], v[6:7], v[38:39], v[40:41]
	v_pk_mul_f32 v[46:47], v[6:7], v[42:43]
	v_pk_mul_f32 v[46:47], v[46:47], v[44:45]
	v_cvt_pk_bf16_f32 v48, v46, v47
	global_store_dword v[22:23], v48, off offset:-1408
	global_load_dword v100, v[12:13], off offset:-3072 nt
	global_load_dword v101, v[14:15], off offset:-3072 nt
	global_load_dword v102, v[20:21], off offset:-3072 nt
	s_waitcnt vmcnt(52)
	v_lshlrev_b32_e32 v24, 16, v109
	v_and_b32_e32 v25, 0xffff0000, v109
	v_lshlrev_b32_e32 v28, 16, v111
	v_and_b32_e32 v29, 0xffff0000, v111
	v_pk_mul_f32 v[24:25], v[24:25], s[56:57] op_sel_hi:[1,0]
	v_pk_mul_f32 v[30:31], v[28:29], s[58:59] op_sel_hi:[1,0]
	v_lshlrev_b32_e32 v26, 16, v110
	v_and_b32_e32 v27, 0xffff0000, v110
	v_exp_f32_e32 v24, v24
	v_exp_f32_e32 v25, v25
	v_exp_f32_e32 v30, v30
	v_exp_f32_e32 v31, v31
	v_pk_add_f32 v[58:59], v[58:59], 1.0 op_sel_hi:[1,0]
	v_rcp_f32_e32 v58, v58
	v_rcp_f32_e32 v59, v59
	v_pk_fma_f32 v[6:7], v[6:7], v[52:53], v[54:55]
	v_pk_mul_f32 v[60:61], v[6:7], v[56:57]
	v_pk_mul_f32 v[60:61], v[60:61], v[58:59]
	v_cvt_pk_bf16_f32 v62, v60, v61
	global_store_dword v[22:23], v62, off offset:-1280
	global_load_dword v103, v[12:13], off offset:-2816 nt
	global_load_dword v104, v[14:15], off offset:-2816 nt
	global_load_dword v105, v[20:21], off offset:-2816 nt
	s_waitcnt vmcnt(52)
	v_lshlrev_b32_e32 v38, 16, v112
	v_and_b32_e32 v39, 0xffff0000, v112
	v_lshlrev_b32_e32 v42, 16, v114
	v_and_b32_e32 v43, 0xffff0000, v114
	v_pk_mul_f32 v[38:39], v[38:39], s[56:57] op_sel_hi:[1,0]
	v_pk_mul_f32 v[44:45], v[42:43], s[58:59] op_sel_hi:[1,0]
	v_lshlrev_b32_e32 v40, 16, v113
	v_and_b32_e32 v41, 0xffff0000, v113
	v_exp_f32_e32 v38, v38
	v_exp_f32_e32 v39, v39
	v_exp_f32_e32 v44, v44
	v_exp_f32_e32 v45, v45
	v_pk_add_f32 v[30:31], v[30:31], 1.0 op_sel_hi:[1,0]
	v_rcp_f32_e32 v30, v30
	v_rcp_f32_e32 v31, v31
	v_pk_fma_f32 v[6:7], v[6:7], v[24:25], v[26:27]
	v_pk_mul_f32 v[32:33], v[6:7], v[28:29]
	v_pk_mul_f32 v[32:33], v[32:33], v[30:31]
	v_cvt_pk_bf16_f32 v34, v32, v33
	global_store_dword v[22:23], v34, off offset:-1152
	global_load_dword v106, v[12:13], off offset:-2560 nt
	global_load_dword v107, v[14:15], off offset:-2560 nt
	global_load_dword v108, v[20:21], off offset:-2560 nt
	s_waitcnt vmcnt(52)
	v_lshlrev_b32_e32 v52, 16, v115
	v_and_b32_e32 v53, 0xffff0000, v115
	v_lshlrev_b32_e32 v56, 16, v117
	v_and_b32_e32 v57, 0xffff0000, v117
	v_pk_mul_f32 v[52:53], v[52:53], s[56:57] op_sel_hi:[1,0]
	v_pk_mul_f32 v[58:59], v[56:57], s[58:59] op_sel_hi:[1,0]
	v_lshlrev_b32_e32 v54, 16, v116
	v_and_b32_e32 v55, 0xffff0000, v116
	v_exp_f32_e32 v52, v52
	v_exp_f32_e32 v53, v53
	v_exp_f32_e32 v58, v58
	v_exp_f32_e32 v59, v59
	v_pk_add_f32 v[44:45], v[44:45], 1.0 op_sel_hi:[1,0]
	v_rcp_f32_e32 v44, v44
	v_rcp_f32_e32 v45, v45
	v_pk_fma_f32 v[6:7], v[6:7], v[38:39], v[40:41]
	v_pk_mul_f32 v[46:47], v[6:7], v[42:43]
	v_pk_mul_f32 v[46:47], v[46:47], v[44:45]
	v_cvt_pk_bf16_f32 v48, v46, v47
	global_store_dword v[22:23], v48, off offset:-1024
	global_load_dword v109, v[12:13], off offset:-2304 nt
	global_load_dword v110, v[14:15], off offset:-2304 nt
	global_load_dword v111, v[20:21], off offset:-2304 nt
	s_waitcnt vmcnt(52)
	v_lshlrev_b32_e32 v24, 16, v118
	v_and_b32_e32 v25, 0xffff0000, v118
	v_lshlrev_b32_e32 v28, 16, v120
	v_and_b32_e32 v29, 0xffff0000, v120
	v_pk_mul_f32 v[24:25], v[24:25], s[56:57] op_sel_hi:[1,0]
	v_pk_mul_f32 v[30:31], v[28:29], s[58:59] op_sel_hi:[1,0]
	v_lshlrev_b32_e32 v26, 16, v119
	v_and_b32_e32 v27, 0xffff0000, v119
	v_exp_f32_e32 v24, v24
	v_exp_f32_e32 v25, v25
	v_exp_f32_e32 v30, v30
	v_exp_f32_e32 v31, v31
	v_pk_add_f32 v[58:59], v[58:59], 1.0 op_sel_hi:[1,0]
	v_rcp_f32_e32 v58, v58
	v_rcp_f32_e32 v59, v59
	v_pk_fma_f32 v[6:7], v[6:7], v[52:53], v[54:55]
	v_pk_mul_f32 v[60:61], v[6:7], v[56:57]
	v_pk_mul_f32 v[60:61], v[60:61], v[58:59]
	v_cvt_pk_bf16_f32 v62, v60, v61
	global_store_dword v[22:23], v62, off offset:-896
	global_load_dword v112, v[12:13], off offset:-2048 nt
	global_load_dword v113, v[14:15], off offset:-2048 nt
	global_load_dword v114, v[20:21], off offset:-2048 nt
	s_waitcnt vmcnt(52)
	v_lshlrev_b32_e32 v38, 16, v121
	v_and_b32_e32 v39, 0xffff0000, v121
	v_lshlrev_b32_e32 v42, 16, v123
	v_and_b32_e32 v43, 0xffff0000, v123
	v_pk_mul_f32 v[38:39], v[38:39], s[56:57] op_sel_hi:[1,0]
	v_pk_mul_f32 v[44:45], v[42:43], s[58:59] op_sel_hi:[1,0]
	v_lshlrev_b32_e32 v40, 16, v122
	v_and_b32_e32 v41, 0xffff0000, v122
	v_exp_f32_e32 v38, v38
	v_exp_f32_e32 v39, v39
	v_exp_f32_e32 v44, v44
	v_exp_f32_e32 v45, v45
	v_pk_add_f32 v[30:31], v[30:31], 1.0 op_sel_hi:[1,0]
	v_rcp_f32_e32 v30, v30
	v_rcp_f32_e32 v31, v31
	v_pk_fma_f32 v[6:7], v[6:7], v[24:25], v[26:27]
	v_pk_mul_f32 v[32:33], v[6:7], v[28:29]
	v_pk_mul_f32 v[32:33], v[32:33], v[30:31]
	v_cvt_pk_bf16_f32 v34, v32, v33
	global_store_dword v[22:23], v34, off offset:-768
	global_load_dword v115, v[12:13], off offset:-1792 nt
	global_load_dword v116, v[14:15], off offset:-1792 nt
	global_load_dword v117, v[20:21], off offset:-1792 nt
	s_waitcnt vmcnt(52)
	v_lshlrev_b32_e32 v52, 16, v124
	v_and_b32_e32 v53, 0xffff0000, v124
	v_lshlrev_b32_e32 v56, 16, v126
	v_and_b32_e32 v57, 0xffff0000, v126
	v_pk_mul_f32 v[52:53], v[52:53], s[56:57] op_sel_hi:[1,0]
	v_pk_mul_f32 v[58:59], v[56:57], s[58:59] op_sel_hi:[1,0]
	v_lshlrev_b32_e32 v54, 16, v125
	v_and_b32_e32 v55, 0xffff0000, v125
	v_exp_f32_e32 v52, v52
	v_exp_f32_e32 v53, v53
	v_exp_f32_e32 v58, v58
	v_exp_f32_e32 v59, v59
	v_pk_add_f32 v[44:45], v[44:45], 1.0 op_sel_hi:[1,0]
	v_rcp_f32_e32 v44, v44
	v_rcp_f32_e32 v45, v45
	v_pk_fma_f32 v[6:7], v[6:7], v[38:39], v[40:41]
	v_pk_mul_f32 v[46:47], v[6:7], v[42:43]
	v_pk_mul_f32 v[46:47], v[46:47], v[44:45]
	v_cvt_pk_bf16_f32 v48, v46, v47
	global_store_dword v[22:23], v48, off offset:-640
	global_load_dword v118, v[12:13], off offset:-1536 nt
	global_load_dword v119, v[14:15], off offset:-1536 nt
	global_load_dword v120, v[20:21], off offset:-1536 nt
	s_waitcnt vmcnt(52)
	v_lshlrev_b32_e32 v24, 16, v127
	v_and_b32_e32 v25, 0xffff0000, v127
	v_lshlrev_b32_e32 v28, 16, v129
	v_and_b32_e32 v29, 0xffff0000, v129
	v_pk_mul_f32 v[24:25], v[24:25], s[56:57] op_sel_hi:[1,0]
	v_pk_mul_f32 v[30:31], v[28:29], s[58:59] op_sel_hi:[1,0]
	v_lshlrev_b32_e32 v26, 16, v128
	v_and_b32_e32 v27, 0xffff0000, v128
	v_exp_f32_e32 v24, v24
	v_exp_f32_e32 v25, v25
	v_exp_f32_e32 v30, v30
	v_exp_f32_e32 v31, v31
	v_pk_add_f32 v[58:59], v[58:59], 1.0 op_sel_hi:[1,0]
	v_rcp_f32_e32 v58, v58
	v_rcp_f32_e32 v59, v59
	v_pk_fma_f32 v[6:7], v[6:7], v[52:53], v[54:55]
	v_pk_mul_f32 v[60:61], v[6:7], v[56:57]
	v_pk_mul_f32 v[60:61], v[60:61], v[58:59]
	v_cvt_pk_bf16_f32 v62, v60, v61
	global_store_dword v[22:23], v62, off offset:-512
	global_load_dword v121, v[12:13], off offset:-1280 nt
	global_load_dword v122, v[14:15], off offset:-1280 nt
	global_load_dword v123, v[20:21], off offset:-1280 nt
	s_waitcnt vmcnt(52)
	v_lshlrev_b32_e32 v38, 16, v130
	v_and_b32_e32 v39, 0xffff0000, v130
	v_lshlrev_b32_e32 v42, 16, v132
	v_and_b32_e32 v43, 0xffff0000, v132
	v_pk_mul_f32 v[38:39], v[38:39], s[56:57] op_sel_hi:[1,0]
	v_pk_mul_f32 v[44:45], v[42:43], s[58:59] op_sel_hi:[1,0]
	v_lshlrev_b32_e32 v40, 16, v131
	v_and_b32_e32 v41, 0xffff0000, v131
	v_exp_f32_e32 v38, v38
	v_exp_f32_e32 v39, v39
	v_exp_f32_e32 v44, v44
	v_exp_f32_e32 v45, v45
	v_pk_add_f32 v[30:31], v[30:31], 1.0 op_sel_hi:[1,0]
	v_rcp_f32_e32 v30, v30
	v_rcp_f32_e32 v31, v31
	v_pk_fma_f32 v[6:7], v[6:7], v[24:25], v[26:27]
	v_pk_mul_f32 v[32:33], v[6:7], v[28:29]
	v_pk_mul_f32 v[32:33], v[32:33], v[30:31]
	v_cvt_pk_bf16_f32 v34, v32, v33
	global_store_dword v[22:23], v34, off offset:-384
	global_load_dword v124, v[12:13], off offset:-1024 nt
	global_load_dword v125, v[14:15], off offset:-1024 nt
	global_load_dword v126, v[20:21], off offset:-1024 nt
	s_waitcnt vmcnt(52)
	v_lshlrev_b32_e32 v52, 16, v133
	v_and_b32_e32 v53, 0xffff0000, v133
	v_lshlrev_b32_e32 v56, 16, v135
	v_and_b32_e32 v57, 0xffff0000, v135
	v_pk_mul_f32 v[52:53], v[52:53], s[56:57] op_sel_hi:[1,0]
	v_pk_mul_f32 v[58:59], v[56:57], s[58:59] op_sel_hi:[1,0]
	v_lshlrev_b32_e32 v54, 16, v134
	v_and_b32_e32 v55, 0xffff0000, v134
	v_exp_f32_e32 v52, v52
	v_exp_f32_e32 v53, v53
	v_exp_f32_e32 v58, v58
	v_exp_f32_e32 v59, v59
	v_pk_add_f32 v[44:45], v[44:45], 1.0 op_sel_hi:[1,0]
	v_rcp_f32_e32 v44, v44
	v_rcp_f32_e32 v45, v45
	v_pk_fma_f32 v[6:7], v[6:7], v[38:39], v[40:41]
	v_pk_mul_f32 v[46:47], v[6:7], v[42:43]
	v_pk_mul_f32 v[46:47], v[46:47], v[44:45]
	v_cvt_pk_bf16_f32 v48, v46, v47
	global_store_dword v[22:23], v48, off offset:-256
	global_load_dword v127, v[12:13], off offset:-768 nt
	global_load_dword v128, v[14:15], off offset:-768 nt
	global_load_dword v129, v[20:21], off offset:-768 nt
	s_waitcnt vmcnt(52)
	v_lshlrev_b32_e32 v24, 16, v88
	v_and_b32_e32 v25, 0xffff0000, v88
	v_lshlrev_b32_e32 v28, 16, v90
	v_and_b32_e32 v29, 0xffff0000, v90
	v_pk_mul_f32 v[24:25], v[24:25], s[56:57] op_sel_hi:[1,0]
	v_pk_mul_f32 v[30:31], v[28:29], s[58:59] op_sel_hi:[1,0]
	v_lshlrev_b32_e32 v26, 16, v89
	v_and_b32_e32 v27, 0xffff0000, v89
	v_exp_f32_e32 v24, v24
	v_exp_f32_e32 v25, v25
	v_exp_f32_e32 v30, v30
	v_exp_f32_e32 v31, v31
	v_pk_add_f32 v[58:59], v[58:59], 1.0 op_sel_hi:[1,0]
	v_rcp_f32_e32 v58, v58
	v_rcp_f32_e32 v59, v59
	v_pk_fma_f32 v[6:7], v[6:7], v[52:53], v[54:55]
	v_pk_mul_f32 v[60:61], v[6:7], v[56:57]
	v_pk_mul_f32 v[60:61], v[60:61], v[58:59]
	v_cvt_pk_bf16_f32 v62, v60, v61
	global_store_dword v[22:23], v62, off offset:-128
	global_load_dword v130, v[12:13], off offset:-512 nt
	global_load_dword v131, v[14:15], off offset:-512 nt
	global_load_dword v132, v[20:21], off offset:-512 nt
	s_waitcnt vmcnt(52)
	v_lshlrev_b32_e32 v38, 16, v91
	v_and_b32_e32 v39, 0xffff0000, v91
	v_lshlrev_b32_e32 v42, 16, v93
	v_and_b32_e32 v43, 0xffff0000, v93
	v_pk_mul_f32 v[38:39], v[38:39], s[56:57] op_sel_hi:[1,0]
	v_pk_mul_f32 v[44:45], v[42:43], s[58:59] op_sel_hi:[1,0]
	v_lshlrev_b32_e32 v40, 16, v92
	v_and_b32_e32 v41, 0xffff0000, v92
	v_exp_f32_e32 v38, v38
	v_exp_f32_e32 v39, v39
	v_exp_f32_e32 v44, v44
	v_exp_f32_e32 v45, v45
	v_pk_add_f32 v[30:31], v[30:31], 1.0 op_sel_hi:[1,0]
	v_rcp_f32_e32 v30, v30
	v_rcp_f32_e32 v31, v31
	v_pk_fma_f32 v[6:7], v[6:7], v[24:25], v[26:27]
	v_pk_mul_f32 v[32:33], v[6:7], v[28:29]
	v_pk_mul_f32 v[32:33], v[32:33], v[30:31]
	v_cvt_pk_bf16_f32 v34, v32, v33
	global_store_dword v[22:23], v34, off
	global_load_dword v133, v[12:13], off offset:-256 nt
	global_load_dword v134, v[14:15], off offset:-256 nt
	global_load_dword v135, v[20:21], off offset:-256 nt
	s_waitcnt vmcnt(52)
	v_lshlrev_b32_e32 v52, 16, v94
	v_and_b32_e32 v53, 0xffff0000, v94
	v_lshlrev_b32_e32 v56, 16, v96
	v_and_b32_e32 v57, 0xffff0000, v96
	v_pk_mul_f32 v[52:53], v[52:53], s[56:57] op_sel_hi:[1,0]
	v_pk_mul_f32 v[58:59], v[56:57], s[58:59] op_sel_hi:[1,0]
	v_lshlrev_b32_e32 v54, 16, v95
	v_and_b32_e32 v55, 0xffff0000, v95
	v_exp_f32_e32 v52, v52
	v_exp_f32_e32 v53, v53
	v_exp_f32_e32 v58, v58
	v_exp_f32_e32 v59, v59
	v_pk_add_f32 v[44:45], v[44:45], 1.0 op_sel_hi:[1,0]
	v_rcp_f32_e32 v44, v44
	v_rcp_f32_e32 v45, v45
	v_pk_fma_f32 v[6:7], v[6:7], v[38:39], v[40:41]
	v_pk_mul_f32 v[46:47], v[6:7], v[42:43]
	v_pk_mul_f32 v[46:47], v[46:47], v[44:45]
	v_cvt_pk_bf16_f32 v48, v46, v47
	global_store_dword v[22:23], v48, off offset:128
	global_load_dword v88, v[12:13], off nt
	global_load_dword v89, v[14:15], off nt
	global_load_dword v90, v[20:21], off nt
	s_waitcnt vmcnt(52)
	v_lshlrev_b32_e32 v24, 16, v97
	v_and_b32_e32 v25, 0xffff0000, v97
	v_lshlrev_b32_e32 v28, 16, v99
	v_and_b32_e32 v29, 0xffff0000, v99
	v_pk_mul_f32 v[24:25], v[24:25], s[56:57] op_sel_hi:[1,0]
	v_pk_mul_f32 v[30:31], v[28:29], s[58:59] op_sel_hi:[1,0]
	v_lshlrev_b32_e32 v26, 16, v98
	v_and_b32_e32 v27, 0xffff0000, v98
	v_exp_f32_e32 v24, v24
	v_exp_f32_e32 v25, v25
	v_exp_f32_e32 v30, v30
	v_exp_f32_e32 v31, v31
	v_pk_add_f32 v[58:59], v[58:59], 1.0 op_sel_hi:[1,0]
	v_rcp_f32_e32 v58, v58
	v_rcp_f32_e32 v59, v59
	v_pk_fma_f32 v[6:7], v[6:7], v[52:53], v[54:55]
	v_pk_mul_f32 v[60:61], v[6:7], v[56:57]
	v_pk_mul_f32 v[60:61], v[60:61], v[58:59]
	v_cvt_pk_bf16_f32 v62, v60, v61
	global_store_dword v[22:23], v62, off offset:256
	global_load_dword v91, v[12:13], off offset:256 nt
	global_load_dword v92, v[14:15], off offset:256 nt
	global_load_dword v93, v[20:21], off offset:256 nt
	s_waitcnt vmcnt(52)
	v_lshlrev_b32_e32 v38, 16, v100
	v_and_b32_e32 v39, 0xffff0000, v100
	v_lshlrev_b32_e32 v42, 16, v102
	v_and_b32_e32 v43, 0xffff0000, v102
	v_pk_mul_f32 v[38:39], v[38:39], s[56:57] op_sel_hi:[1,0]
	v_pk_mul_f32 v[44:45], v[42:43], s[58:59] op_sel_hi:[1,0]
	v_lshlrev_b32_e32 v40, 16, v101
	v_and_b32_e32 v41, 0xffff0000, v101
	v_exp_f32_e32 v38, v38
	v_exp_f32_e32 v39, v39
	v_exp_f32_e32 v44, v44
	v_exp_f32_e32 v45, v45
	v_pk_add_f32 v[30:31], v[30:31], 1.0 op_sel_hi:[1,0]
	v_rcp_f32_e32 v30, v30
	v_rcp_f32_e32 v31, v31
	v_pk_fma_f32 v[6:7], v[6:7], v[24:25], v[26:27]
	v_pk_mul_f32 v[32:33], v[6:7], v[28:29]
	v_pk_mul_f32 v[32:33], v[32:33], v[30:31]
	v_cvt_pk_bf16_f32 v34, v32, v33
	global_store_dword v[22:23], v34, off offset:384
	global_load_dword v94, v[12:13], off offset:512 nt
	global_load_dword v95, v[14:15], off offset:512 nt
	global_load_dword v96, v[20:21], off offset:512 nt
	s_waitcnt vmcnt(52)
	v_lshlrev_b32_e32 v52, 16, v103
	v_and_b32_e32 v53, 0xffff0000, v103
	v_lshlrev_b32_e32 v56, 16, v105
	v_and_b32_e32 v57, 0xffff0000, v105
	v_pk_mul_f32 v[52:53], v[52:53], s[56:57] op_sel_hi:[1,0]
	v_pk_mul_f32 v[58:59], v[56:57], s[58:59] op_sel_hi:[1,0]
	v_lshlrev_b32_e32 v54, 16, v104
	v_and_b32_e32 v55, 0xffff0000, v104
	v_exp_f32_e32 v52, v52
	v_exp_f32_e32 v53, v53
	v_exp_f32_e32 v58, v58
	v_exp_f32_e32 v59, v59
	v_pk_add_f32 v[44:45], v[44:45], 1.0 op_sel_hi:[1,0]
	v_rcp_f32_e32 v44, v44
	v_rcp_f32_e32 v45, v45
	v_pk_fma_f32 v[6:7], v[6:7], v[38:39], v[40:41]
	v_pk_mul_f32 v[46:47], v[6:7], v[42:43]
	v_pk_mul_f32 v[46:47], v[46:47], v[44:45]
	v_cvt_pk_bf16_f32 v48, v46, v47
	global_store_dword v[22:23], v48, off offset:512
	global_load_dword v97, v[12:13], off offset:768 nt
	global_load_dword v98, v[14:15], off offset:768 nt
	global_load_dword v99, v[20:21], off offset:768 nt
	s_waitcnt vmcnt(52)
	v_lshlrev_b32_e32 v24, 16, v106
	v_and_b32_e32 v25, 0xffff0000, v106
	v_lshlrev_b32_e32 v28, 16, v108
	v_and_b32_e32 v29, 0xffff0000, v108
	v_pk_mul_f32 v[24:25], v[24:25], s[56:57] op_sel_hi:[1,0]
	v_pk_mul_f32 v[30:31], v[28:29], s[58:59] op_sel_hi:[1,0]
	v_lshlrev_b32_e32 v26, 16, v107
	v_and_b32_e32 v27, 0xffff0000, v107
	v_exp_f32_e32 v24, v24
	v_exp_f32_e32 v25, v25
	v_exp_f32_e32 v30, v30
	v_exp_f32_e32 v31, v31
	v_pk_add_f32 v[58:59], v[58:59], 1.0 op_sel_hi:[1,0]
	v_rcp_f32_e32 v58, v58
	v_rcp_f32_e32 v59, v59
	v_pk_fma_f32 v[6:7], v[6:7], v[52:53], v[54:55]
	v_pk_mul_f32 v[60:61], v[6:7], v[56:57]
	v_pk_mul_f32 v[60:61], v[60:61], v[58:59]
	v_cvt_pk_bf16_f32 v62, v60, v61
	global_store_dword v[22:23], v62, off offset:640
	global_load_dword v100, v[12:13], off offset:1024 nt
	global_load_dword v101, v[14:15], off offset:1024 nt
	global_load_dword v102, v[20:21], off offset:1024 nt
	s_waitcnt vmcnt(52)
	v_lshlrev_b32_e32 v38, 16, v109
	v_and_b32_e32 v39, 0xffff0000, v109
	v_lshlrev_b32_e32 v42, 16, v111
	v_and_b32_e32 v43, 0xffff0000, v111
	v_pk_mul_f32 v[38:39], v[38:39], s[56:57] op_sel_hi:[1,0]
	v_pk_mul_f32 v[44:45], v[42:43], s[58:59] op_sel_hi:[1,0]
	v_lshlrev_b32_e32 v40, 16, v110
	v_and_b32_e32 v41, 0xffff0000, v110
	v_exp_f32_e32 v38, v38
	v_exp_f32_e32 v39, v39
	v_exp_f32_e32 v44, v44
	v_exp_f32_e32 v45, v45
	v_pk_add_f32 v[30:31], v[30:31], 1.0 op_sel_hi:[1,0]
	v_rcp_f32_e32 v30, v30
	v_rcp_f32_e32 v31, v31
	v_pk_fma_f32 v[6:7], v[6:7], v[24:25], v[26:27]
	v_pk_mul_f32 v[32:33], v[6:7], v[28:29]
	v_pk_mul_f32 v[32:33], v[32:33], v[30:31]
	v_cvt_pk_bf16_f32 v34, v32, v33
	global_store_dword v[22:23], v34, off offset:768
	global_load_dword v103, v[12:13], off offset:1280 nt
	global_load_dword v104, v[14:15], off offset:1280 nt
	global_load_dword v105, v[20:21], off offset:1280 nt
	s_waitcnt vmcnt(52)
	v_lshlrev_b32_e32 v52, 16, v112
	v_and_b32_e32 v53, 0xffff0000, v112
	v_lshlrev_b32_e32 v56, 16, v114
	v_and_b32_e32 v57, 0xffff0000, v114
	v_pk_mul_f32 v[52:53], v[52:53], s[56:57] op_sel_hi:[1,0]
	v_pk_mul_f32 v[58:59], v[56:57], s[58:59] op_sel_hi:[1,0]
	v_lshlrev_b32_e32 v54, 16, v113
	v_and_b32_e32 v55, 0xffff0000, v113
	v_exp_f32_e32 v52, v52
	v_exp_f32_e32 v53, v53
	v_exp_f32_e32 v58, v58
	v_exp_f32_e32 v59, v59
	v_pk_add_f32 v[44:45], v[44:45], 1.0 op_sel_hi:[1,0]
	v_rcp_f32_e32 v44, v44
	v_rcp_f32_e32 v45, v45
	v_pk_fma_f32 v[6:7], v[6:7], v[38:39], v[40:41]
	v_pk_mul_f32 v[46:47], v[6:7], v[42:43]
	v_pk_mul_f32 v[46:47], v[46:47], v[44:45]
	v_cvt_pk_bf16_f32 v48, v46, v47
	global_store_dword v[22:23], v48, off offset:896
	global_load_dword v106, v[12:13], off offset:1536 nt
	global_load_dword v107, v[14:15], off offset:1536 nt
	global_load_dword v108, v[20:21], off offset:1536 nt
	s_waitcnt vmcnt(52)
	v_lshlrev_b32_e32 v24, 16, v115
	v_and_b32_e32 v25, 0xffff0000, v115
	v_lshlrev_b32_e32 v28, 16, v117
	v_and_b32_e32 v29, 0xffff0000, v117
	v_pk_mul_f32 v[24:25], v[24:25], s[56:57] op_sel_hi:[1,0]
	v_pk_mul_f32 v[30:31], v[28:29], s[58:59] op_sel_hi:[1,0]
	v_lshlrev_b32_e32 v26, 16, v116
	v_and_b32_e32 v27, 0xffff0000, v116
	v_exp_f32_e32 v24, v24
	v_exp_f32_e32 v25, v25
	v_exp_f32_e32 v30, v30
	v_exp_f32_e32 v31, v31
	v_pk_add_f32 v[58:59], v[58:59], 1.0 op_sel_hi:[1,0]
	v_rcp_f32_e32 v58, v58
	v_rcp_f32_e32 v59, v59
	v_pk_fma_f32 v[6:7], v[6:7], v[52:53], v[54:55]
	v_pk_mul_f32 v[60:61], v[6:7], v[56:57]
	v_pk_mul_f32 v[60:61], v[60:61], v[58:59]
	v_cvt_pk_bf16_f32 v62, v60, v61
	global_store_dword v[22:23], v62, off offset:1024
	global_load_dword v109, v[12:13], off offset:1792 nt
	global_load_dword v110, v[14:15], off offset:1792 nt
	global_load_dword v111, v[20:21], off offset:1792 nt
	s_waitcnt vmcnt(52)
	v_lshlrev_b32_e32 v38, 16, v118
	v_and_b32_e32 v39, 0xffff0000, v118
	v_lshlrev_b32_e32 v42, 16, v120
	v_and_b32_e32 v43, 0xffff0000, v120
	v_pk_mul_f32 v[38:39], v[38:39], s[56:57] op_sel_hi:[1,0]
	v_pk_mul_f32 v[44:45], v[42:43], s[58:59] op_sel_hi:[1,0]
	v_lshlrev_b32_e32 v40, 16, v119
	v_and_b32_e32 v41, 0xffff0000, v119
	v_exp_f32_e32 v38, v38
	v_exp_f32_e32 v39, v39
	v_exp_f32_e32 v44, v44
	v_exp_f32_e32 v45, v45
	v_pk_add_f32 v[30:31], v[30:31], 1.0 op_sel_hi:[1,0]
	v_rcp_f32_e32 v30, v30
	v_rcp_f32_e32 v31, v31
	v_pk_fma_f32 v[6:7], v[6:7], v[24:25], v[26:27]
	v_pk_mul_f32 v[32:33], v[6:7], v[28:29]
	v_pk_mul_f32 v[32:33], v[32:33], v[30:31]
	v_cvt_pk_bf16_f32 v34, v32, v33
	global_store_dword v[22:23], v34, off offset:1152
	global_load_dword v112, v[12:13], off offset:2048 nt
	global_load_dword v113, v[14:15], off offset:2048 nt
	global_load_dword v114, v[20:21], off offset:2048 nt
	s_waitcnt vmcnt(52)
	v_lshlrev_b32_e32 v52, 16, v121
	v_and_b32_e32 v53, 0xffff0000, v121
	v_lshlrev_b32_e32 v56, 16, v123
	v_and_b32_e32 v57, 0xffff0000, v123
	v_pk_mul_f32 v[52:53], v[52:53], s[56:57] op_sel_hi:[1,0]
	v_pk_mul_f32 v[58:59], v[56:57], s[58:59] op_sel_hi:[1,0]
	v_lshlrev_b32_e32 v54, 16, v122
	v_and_b32_e32 v55, 0xffff0000, v122
	v_exp_f32_e32 v52, v52
	v_exp_f32_e32 v53, v53
	v_exp_f32_e32 v58, v58
	v_exp_f32_e32 v59, v59
	v_pk_add_f32 v[44:45], v[44:45], 1.0 op_sel_hi:[1,0]
	v_rcp_f32_e32 v44, v44
	v_rcp_f32_e32 v45, v45
	v_pk_fma_f32 v[6:7], v[6:7], v[38:39], v[40:41]
	v_pk_mul_f32 v[46:47], v[6:7], v[42:43]
	v_pk_mul_f32 v[46:47], v[46:47], v[44:45]
	v_cvt_pk_bf16_f32 v48, v46, v47
	global_store_dword v[22:23], v48, off offset:1280
	global_load_dword v115, v[12:13], off offset:2304 nt
	global_load_dword v116, v[14:15], off offset:2304 nt
	global_load_dword v117, v[20:21], off offset:2304 nt
	s_waitcnt vmcnt(52)
	v_lshlrev_b32_e32 v24, 16, v124
	v_and_b32_e32 v25, 0xffff0000, v124
	v_lshlrev_b32_e32 v28, 16, v126
	v_and_b32_e32 v29, 0xffff0000, v126
	v_pk_mul_f32 v[24:25], v[24:25], s[56:57] op_sel_hi:[1,0]
	v_pk_mul_f32 v[30:31], v[28:29], s[58:59] op_sel_hi:[1,0]
	v_lshlrev_b32_e32 v26, 16, v125
	v_and_b32_e32 v27, 0xffff0000, v125
	v_exp_f32_e32 v24, v24
	v_exp_f32_e32 v25, v25
	v_exp_f32_e32 v30, v30
	v_exp_f32_e32 v31, v31
	v_pk_add_f32 v[58:59], v[58:59], 1.0 op_sel_hi:[1,0]
	v_rcp_f32_e32 v58, v58
	v_rcp_f32_e32 v59, v59
	v_pk_fma_f32 v[6:7], v[6:7], v[52:53], v[54:55]
	v_pk_mul_f32 v[60:61], v[6:7], v[56:57]
	v_pk_mul_f32 v[60:61], v[60:61], v[58:59]
	v_cvt_pk_bf16_f32 v62, v60, v61
	global_store_dword v[22:23], v62, off offset:1408
	global_load_dword v118, v[12:13], off offset:2560 nt
	global_load_dword v119, v[14:15], off offset:2560 nt
	global_load_dword v120, v[20:21], off offset:2560 nt
	s_waitcnt vmcnt(52)
	v_lshlrev_b32_e32 v38, 16, v127
	v_and_b32_e32 v39, 0xffff0000, v127
	v_lshlrev_b32_e32 v42, 16, v129
	v_and_b32_e32 v43, 0xffff0000, v129
	v_pk_mul_f32 v[38:39], v[38:39], s[56:57] op_sel_hi:[1,0]
	v_pk_mul_f32 v[44:45], v[42:43], s[58:59] op_sel_hi:[1,0]
	v_lshlrev_b32_e32 v40, 16, v128
	v_and_b32_e32 v41, 0xffff0000, v128
	v_exp_f32_e32 v38, v38
	v_exp_f32_e32 v39, v39
	v_exp_f32_e32 v44, v44
	v_exp_f32_e32 v45, v45
	v_pk_add_f32 v[30:31], v[30:31], 1.0 op_sel_hi:[1,0]
	v_rcp_f32_e32 v30, v30
	v_rcp_f32_e32 v31, v31
	v_pk_fma_f32 v[6:7], v[6:7], v[24:25], v[26:27]
	v_pk_mul_f32 v[32:33], v[6:7], v[28:29]
	v_pk_mul_f32 v[32:33], v[32:33], v[30:31]
	v_cvt_pk_bf16_f32 v34, v32, v33
	global_store_dword v[22:23], v34, off offset:1536
	global_load_dword v121, v[12:13], off offset:2816 nt
	global_load_dword v122, v[14:15], off offset:2816 nt
	global_load_dword v123, v[20:21], off offset:2816 nt
	s_waitcnt vmcnt(52)
	v_lshlrev_b32_e32 v52, 16, v130
	v_and_b32_e32 v53, 0xffff0000, v130
	v_lshlrev_b32_e32 v56, 16, v132
	v_and_b32_e32 v57, 0xffff0000, v132
	v_pk_mul_f32 v[52:53], v[52:53], s[56:57] op_sel_hi:[1,0]
	v_pk_mul_f32 v[58:59], v[56:57], s[58:59] op_sel_hi:[1,0]
	v_lshlrev_b32_e32 v54, 16, v131
	v_and_b32_e32 v55, 0xffff0000, v131
	v_exp_f32_e32 v52, v52
	v_exp_f32_e32 v53, v53
	v_exp_f32_e32 v58, v58
	v_exp_f32_e32 v59, v59
	v_pk_add_f32 v[44:45], v[44:45], 1.0 op_sel_hi:[1,0]
	v_rcp_f32_e32 v44, v44
	v_rcp_f32_e32 v45, v45
	v_pk_fma_f32 v[6:7], v[6:7], v[38:39], v[40:41]
	v_pk_mul_f32 v[46:47], v[6:7], v[42:43]
	v_pk_mul_f32 v[46:47], v[46:47], v[44:45]
	v_cvt_pk_bf16_f32 v48, v46, v47
	global_store_dword v[22:23], v48, off offset:1664
	global_load_dword v124, v[12:13], off offset:3072 nt
	global_load_dword v125, v[14:15], off offset:3072 nt
	global_load_dword v126, v[20:21], off offset:3072 nt
	s_waitcnt vmcnt(52)
	v_lshlrev_b32_e32 v24, 16, v133
	v_and_b32_e32 v25, 0xffff0000, v133
	v_lshlrev_b32_e32 v28, 16, v135
	v_and_b32_e32 v29, 0xffff0000, v135
	v_pk_mul_f32 v[24:25], v[24:25], s[56:57] op_sel_hi:[1,0]
	v_pk_mul_f32 v[30:31], v[28:29], s[58:59] op_sel_hi:[1,0]
	v_lshlrev_b32_e32 v26, 16, v134
	v_and_b32_e32 v27, 0xffff0000, v134
	v_exp_f32_e32 v24, v24
	v_exp_f32_e32 v25, v25
	v_exp_f32_e32 v30, v30
	v_exp_f32_e32 v31, v31
	v_pk_add_f32 v[58:59], v[58:59], 1.0 op_sel_hi:[1,0]
	v_rcp_f32_e32 v58, v58
	v_rcp_f32_e32 v59, v59
	v_pk_fma_f32 v[6:7], v[6:7], v[52:53], v[54:55]
	v_pk_mul_f32 v[60:61], v[6:7], v[56:57]
	v_pk_mul_f32 v[60:61], v[60:61], v[58:59]
	v_cvt_pk_bf16_f32 v62, v60, v61
	global_store_dword v[22:23], v62, off offset:1792
	global_load_dword v127, v[12:13], off offset:3328 nt
	global_load_dword v128, v[14:15], off offset:3328 nt
	global_load_dword v129, v[20:21], off offset:3328 nt
	s_waitcnt vmcnt(52)
	v_lshlrev_b32_e32 v38, 16, v88
	v_and_b32_e32 v39, 0xffff0000, v88
	v_lshlrev_b32_e32 v42, 16, v90
	v_and_b32_e32 v43, 0xffff0000, v90
	v_pk_mul_f32 v[38:39], v[38:39], s[56:57] op_sel_hi:[1,0]
	v_pk_mul_f32 v[44:45], v[42:43], s[58:59] op_sel_hi:[1,0]
	v_lshlrev_b32_e32 v40, 16, v89
	v_and_b32_e32 v41, 0xffff0000, v89
	v_exp_f32_e32 v38, v38
	v_exp_f32_e32 v39, v39
	v_exp_f32_e32 v44, v44
	v_exp_f32_e32 v45, v45
	v_pk_add_f32 v[30:31], v[30:31], 1.0 op_sel_hi:[1,0]
	v_rcp_f32_e32 v30, v30
	v_rcp_f32_e32 v31, v31
	v_pk_fma_f32 v[6:7], v[6:7], v[24:25], v[26:27]
	v_pk_mul_f32 v[32:33], v[6:7], v[28:29]
	v_pk_mul_f32 v[32:33], v[32:33], v[30:31]
	v_cvt_pk_bf16_f32 v34, v32, v33
	global_store_dword v[22:23], v34, off offset:1920
	global_load_dword v130, v[12:13], off offset:3584 nt
	global_load_dword v131, v[14:15], off offset:3584 nt
	global_load_dword v132, v[20:21], off offset:3584 nt
	s_waitcnt vmcnt(52)
	v_lshlrev_b32_e32 v52, 16, v91
	v_and_b32_e32 v53, 0xffff0000, v91
	v_lshlrev_b32_e32 v56, 16, v93
	v_and_b32_e32 v57, 0xffff0000, v93
	v_pk_mul_f32 v[52:53], v[52:53], s[56:57] op_sel_hi:[1,0]
	v_pk_mul_f32 v[58:59], v[56:57], s[58:59] op_sel_hi:[1,0]
	v_lshlrev_b32_e32 v54, 16, v92
	v_and_b32_e32 v55, 0xffff0000, v92
	v_exp_f32_e32 v52, v52
	v_exp_f32_e32 v53, v53
	v_exp_f32_e32 v58, v58
	v_exp_f32_e32 v59, v59
	v_pk_add_f32 v[44:45], v[44:45], 1.0 op_sel_hi:[1,0]
	v_rcp_f32_e32 v44, v44
	v_rcp_f32_e32 v45, v45
	v_pk_fma_f32 v[6:7], v[6:7], v[38:39], v[40:41]
	v_pk_mul_f32 v[46:47], v[6:7], v[42:43]
	v_pk_mul_f32 v[46:47], v[46:47], v[44:45]
	v_cvt_pk_bf16_f32 v48, v46, v47
	global_store_dword v[22:23], v48, off offset:2048
	global_load_dword v133, v[12:13], off offset:3840 nt
	global_load_dword v134, v[14:15], off offset:3840 nt
	global_load_dword v135, v[20:21], off offset:3840 nt
	s_waitcnt vmcnt(52)
	v_lshlrev_b32_e32 v24, 16, v94
	v_and_b32_e32 v25, 0xffff0000, v94
	v_lshlrev_b32_e32 v28, 16, v96
	v_and_b32_e32 v29, 0xffff0000, v96
	v_pk_mul_f32 v[24:25], v[24:25], s[56:57] op_sel_hi:[1,0]
	v_pk_mul_f32 v[30:31], v[28:29], s[58:59] op_sel_hi:[1,0]
	v_lshlrev_b32_e32 v26, 16, v95
	v_and_b32_e32 v27, 0xffff0000, v95
	v_exp_f32_e32 v24, v24
	v_exp_f32_e32 v25, v25
	v_exp_f32_e32 v30, v30
	v_exp_f32_e32 v31, v31
	v_pk_add_f32 v[58:59], v[58:59], 1.0 op_sel_hi:[1,0]
	v_rcp_f32_e32 v58, v58
	v_rcp_f32_e32 v59, v59
	v_pk_fma_f32 v[6:7], v[6:7], v[52:53], v[54:55]
	v_pk_mul_f32 v[60:61], v[6:7], v[56:57]
	v_pk_mul_f32 v[60:61], v[60:61], v[58:59]
	v_cvt_pk_bf16_f32 v62, v60, v61
	global_store_dword v[22:23], v62, off offset:2176
	s_waitcnt vmcnt(49)
	v_lshlrev_b32_e32 v38, 16, v97
	v_and_b32_e32 v39, 0xffff0000, v97
	v_lshlrev_b32_e32 v42, 16, v99
	v_and_b32_e32 v43, 0xffff0000, v99
	v_pk_mul_f32 v[38:39], v[38:39], s[56:57] op_sel_hi:[1,0]
	v_pk_mul_f32 v[44:45], v[42:43], s[58:59] op_sel_hi:[1,0]
	v_lshlrev_b32_e32 v40, 16, v98
	v_and_b32_e32 v41, 0xffff0000, v98
	v_exp_f32_e32 v38, v38
	v_exp_f32_e32 v39, v39
	v_exp_f32_e32 v44, v44
	v_exp_f32_e32 v45, v45
	v_pk_add_f32 v[30:31], v[30:31], 1.0 op_sel_hi:[1,0]
	v_rcp_f32_e32 v30, v30
	v_rcp_f32_e32 v31, v31
	v_pk_fma_f32 v[6:7], v[6:7], v[24:25], v[26:27]
	v_pk_mul_f32 v[32:33], v[6:7], v[28:29]
	v_pk_mul_f32 v[32:33], v[32:33], v[30:31]
	v_cvt_pk_bf16_f32 v34, v32, v33
	global_store_dword v[22:23], v34, off offset:2304
	s_waitcnt vmcnt(46)
	v_lshlrev_b32_e32 v52, 16, v100
	v_and_b32_e32 v53, 0xffff0000, v100
	v_lshlrev_b32_e32 v56, 16, v102
	v_and_b32_e32 v57, 0xffff0000, v102
	v_pk_mul_f32 v[52:53], v[52:53], s[56:57] op_sel_hi:[1,0]
	v_pk_mul_f32 v[58:59], v[56:57], s[58:59] op_sel_hi:[1,0]
	v_lshlrev_b32_e32 v54, 16, v101
	v_and_b32_e32 v55, 0xffff0000, v101
	v_exp_f32_e32 v52, v52
	v_exp_f32_e32 v53, v53
	v_exp_f32_e32 v58, v58
	v_exp_f32_e32 v59, v59
	v_pk_add_f32 v[44:45], v[44:45], 1.0 op_sel_hi:[1,0]
	v_rcp_f32_e32 v44, v44
	v_rcp_f32_e32 v45, v45
	v_pk_fma_f32 v[6:7], v[6:7], v[38:39], v[40:41]
	v_pk_mul_f32 v[46:47], v[6:7], v[42:43]
	v_pk_mul_f32 v[46:47], v[46:47], v[44:45]
	v_cvt_pk_bf16_f32 v48, v46, v47
	global_store_dword v[22:23], v48, off offset:2432
	s_waitcnt vmcnt(43)
	v_lshlrev_b32_e32 v24, 16, v103
	v_and_b32_e32 v25, 0xffff0000, v103
	v_lshlrev_b32_e32 v28, 16, v105
	v_and_b32_e32 v29, 0xffff0000, v105
	v_pk_mul_f32 v[24:25], v[24:25], s[56:57] op_sel_hi:[1,0]
	v_pk_mul_f32 v[30:31], v[28:29], s[58:59] op_sel_hi:[1,0]
	v_lshlrev_b32_e32 v26, 16, v104
	v_and_b32_e32 v27, 0xffff0000, v104
	v_exp_f32_e32 v24, v24
	v_exp_f32_e32 v25, v25
	v_exp_f32_e32 v30, v30
	v_exp_f32_e32 v31, v31
	v_pk_add_f32 v[58:59], v[58:59], 1.0 op_sel_hi:[1,0]
	v_rcp_f32_e32 v58, v58
	v_rcp_f32_e32 v59, v59
	v_pk_fma_f32 v[6:7], v[6:7], v[52:53], v[54:55]
	v_pk_mul_f32 v[60:61], v[6:7], v[56:57]
	v_pk_mul_f32 v[60:61], v[60:61], v[58:59]
	v_cvt_pk_bf16_f32 v62, v60, v61
	global_store_dword v[22:23], v62, off offset:2560
	s_waitcnt vmcnt(40)
	v_lshlrev_b32_e32 v38, 16, v106
	v_and_b32_e32 v39, 0xffff0000, v106
	v_lshlrev_b32_e32 v42, 16, v108
	v_and_b32_e32 v43, 0xffff0000, v108
	v_pk_mul_f32 v[38:39], v[38:39], s[56:57] op_sel_hi:[1,0]
	v_pk_mul_f32 v[44:45], v[42:43], s[58:59] op_sel_hi:[1,0]
	v_lshlrev_b32_e32 v40, 16, v107
	v_and_b32_e32 v41, 0xffff0000, v107
	v_exp_f32_e32 v38, v38
	v_exp_f32_e32 v39, v39
	v_exp_f32_e32 v44, v44
	v_exp_f32_e32 v45, v45
	v_pk_add_f32 v[30:31], v[30:31], 1.0 op_sel_hi:[1,0]
	v_rcp_f32_e32 v30, v30
	v_rcp_f32_e32 v31, v31
	v_pk_fma_f32 v[6:7], v[6:7], v[24:25], v[26:27]
	v_pk_mul_f32 v[32:33], v[6:7], v[28:29]
	v_pk_mul_f32 v[32:33], v[32:33], v[30:31]
	v_cvt_pk_bf16_f32 v34, v32, v33
	global_store_dword v[22:23], v34, off offset:2688
	s_waitcnt vmcnt(37)
	v_lshlrev_b32_e32 v52, 16, v109
	v_and_b32_e32 v53, 0xffff0000, v109
	v_lshlrev_b32_e32 v56, 16, v111
	v_and_b32_e32 v57, 0xffff0000, v111
	v_pk_mul_f32 v[52:53], v[52:53], s[56:57] op_sel_hi:[1,0]
	v_pk_mul_f32 v[58:59], v[56:57], s[58:59] op_sel_hi:[1,0]
	v_lshlrev_b32_e32 v54, 16, v110
	v_and_b32_e32 v55, 0xffff0000, v110
	v_exp_f32_e32 v52, v52
	v_exp_f32_e32 v53, v53
	v_exp_f32_e32 v58, v58
	v_exp_f32_e32 v59, v59
	v_pk_add_f32 v[44:45], v[44:45], 1.0 op_sel_hi:[1,0]
	v_rcp_f32_e32 v44, v44
	v_rcp_f32_e32 v45, v45
	v_pk_fma_f32 v[6:7], v[6:7], v[38:39], v[40:41]
	v_pk_mul_f32 v[46:47], v[6:7], v[42:43]
	v_pk_mul_f32 v[46:47], v[46:47], v[44:45]
	v_cvt_pk_bf16_f32 v48, v46, v47
	global_store_dword v[22:23], v48, off offset:2816
	s_waitcnt vmcnt(34)
	v_lshlrev_b32_e32 v24, 16, v112
	v_and_b32_e32 v25, 0xffff0000, v112
	v_lshlrev_b32_e32 v28, 16, v114
	v_and_b32_e32 v29, 0xffff0000, v114
	v_pk_mul_f32 v[24:25], v[24:25], s[56:57] op_sel_hi:[1,0]
	v_pk_mul_f32 v[30:31], v[28:29], s[58:59] op_sel_hi:[1,0]
	v_lshlrev_b32_e32 v26, 16, v113
	v_and_b32_e32 v27, 0xffff0000, v113
	v_exp_f32_e32 v24, v24
	v_exp_f32_e32 v25, v25
	v_exp_f32_e32 v30, v30
	v_exp_f32_e32 v31, v31
	v_pk_add_f32 v[58:59], v[58:59], 1.0 op_sel_hi:[1,0]
	v_rcp_f32_e32 v58, v58
	v_rcp_f32_e32 v59, v59
	v_pk_fma_f32 v[6:7], v[6:7], v[52:53], v[54:55]
	v_pk_mul_f32 v[60:61], v[6:7], v[56:57]
	v_pk_mul_f32 v[60:61], v[60:61], v[58:59]
	v_cvt_pk_bf16_f32 v62, v60, v61
	global_store_dword v[22:23], v62, off offset:2944
	s_waitcnt vmcnt(31)
	v_lshlrev_b32_e32 v38, 16, v115
	v_and_b32_e32 v39, 0xffff0000, v115
	v_lshlrev_b32_e32 v42, 16, v117
	v_and_b32_e32 v43, 0xffff0000, v117
	v_pk_mul_f32 v[38:39], v[38:39], s[56:57] op_sel_hi:[1,0]
	v_pk_mul_f32 v[44:45], v[42:43], s[58:59] op_sel_hi:[1,0]
	v_lshlrev_b32_e32 v40, 16, v116
	v_and_b32_e32 v41, 0xffff0000, v116
	v_exp_f32_e32 v38, v38
	v_exp_f32_e32 v39, v39
	v_exp_f32_e32 v44, v44
	v_exp_f32_e32 v45, v45
	v_pk_add_f32 v[30:31], v[30:31], 1.0 op_sel_hi:[1,0]
	v_rcp_f32_e32 v30, v30
	v_rcp_f32_e32 v31, v31
	v_pk_fma_f32 v[6:7], v[6:7], v[24:25], v[26:27]
	v_pk_mul_f32 v[32:33], v[6:7], v[28:29]
	v_pk_mul_f32 v[32:33], v[32:33], v[30:31]
	v_cvt_pk_bf16_f32 v34, v32, v33
	global_store_dword v[22:23], v34, off offset:3072
	s_waitcnt vmcnt(28)
	v_lshlrev_b32_e32 v52, 16, v118
	v_and_b32_e32 v53, 0xffff0000, v118
	v_lshlrev_b32_e32 v56, 16, v120
	v_and_b32_e32 v57, 0xffff0000, v120
	v_pk_mul_f32 v[52:53], v[52:53], s[56:57] op_sel_hi:[1,0]
	v_pk_mul_f32 v[58:59], v[56:57], s[58:59] op_sel_hi:[1,0]
	v_lshlrev_b32_e32 v54, 16, v119
	v_and_b32_e32 v55, 0xffff0000, v119
	v_exp_f32_e32 v52, v52
	v_exp_f32_e32 v53, v53
	v_exp_f32_e32 v58, v58
	v_exp_f32_e32 v59, v59
	v_pk_add_f32 v[44:45], v[44:45], 1.0 op_sel_hi:[1,0]
	v_rcp_f32_e32 v44, v44
	v_rcp_f32_e32 v45, v45
	v_pk_fma_f32 v[6:7], v[6:7], v[38:39], v[40:41]
	v_pk_mul_f32 v[46:47], v[6:7], v[42:43]
	v_pk_mul_f32 v[46:47], v[46:47], v[44:45]
	v_cvt_pk_bf16_f32 v48, v46, v47
	global_store_dword v[22:23], v48, off offset:3200
	s_waitcnt vmcnt(25)
	v_lshlrev_b32_e32 v24, 16, v121
	v_and_b32_e32 v25, 0xffff0000, v121
	v_lshlrev_b32_e32 v28, 16, v123
	v_and_b32_e32 v29, 0xffff0000, v123
	v_pk_mul_f32 v[24:25], v[24:25], s[56:57] op_sel_hi:[1,0]
	v_pk_mul_f32 v[30:31], v[28:29], s[58:59] op_sel_hi:[1,0]
	v_lshlrev_b32_e32 v26, 16, v122
	v_and_b32_e32 v27, 0xffff0000, v122
	v_exp_f32_e32 v24, v24
	v_exp_f32_e32 v25, v25
	v_exp_f32_e32 v30, v30
	v_exp_f32_e32 v31, v31
	v_pk_add_f32 v[58:59], v[58:59], 1.0 op_sel_hi:[1,0]
	v_rcp_f32_e32 v58, v58
	v_rcp_f32_e32 v59, v59
	v_pk_fma_f32 v[6:7], v[6:7], v[52:53], v[54:55]
	v_pk_mul_f32 v[60:61], v[6:7], v[56:57]
	v_pk_mul_f32 v[60:61], v[60:61], v[58:59]
	v_cvt_pk_bf16_f32 v62, v60, v61
	global_store_dword v[22:23], v62, off offset:3328
	s_waitcnt vmcnt(22)
	v_lshlrev_b32_e32 v38, 16, v124
	v_and_b32_e32 v39, 0xffff0000, v124
	v_lshlrev_b32_e32 v42, 16, v126
	v_and_b32_e32 v43, 0xffff0000, v126
	v_pk_mul_f32 v[38:39], v[38:39], s[56:57] op_sel_hi:[1,0]
	v_pk_mul_f32 v[44:45], v[42:43], s[58:59] op_sel_hi:[1,0]
	v_lshlrev_b32_e32 v40, 16, v125
	v_and_b32_e32 v41, 0xffff0000, v125
	v_exp_f32_e32 v38, v38
	v_exp_f32_e32 v39, v39
	v_exp_f32_e32 v44, v44
	v_exp_f32_e32 v45, v45
	v_pk_add_f32 v[30:31], v[30:31], 1.0 op_sel_hi:[1,0]
	v_rcp_f32_e32 v30, v30
	v_rcp_f32_e32 v31, v31
	v_pk_fma_f32 v[6:7], v[6:7], v[24:25], v[26:27]
	v_pk_mul_f32 v[32:33], v[6:7], v[28:29]
	v_pk_mul_f32 v[32:33], v[32:33], v[30:31]
	v_cvt_pk_bf16_f32 v34, v32, v33
	global_store_dword v[22:23], v34, off offset:3456
	s_waitcnt vmcnt(19)
	v_lshlrev_b32_e32 v52, 16, v127
	v_and_b32_e32 v53, 0xffff0000, v127
	v_lshlrev_b32_e32 v56, 16, v129
	v_and_b32_e32 v57, 0xffff0000, v129
	v_pk_mul_f32 v[52:53], v[52:53], s[56:57] op_sel_hi:[1,0]
	v_pk_mul_f32 v[58:59], v[56:57], s[58:59] op_sel_hi:[1,0]
	v_lshlrev_b32_e32 v54, 16, v128
	v_and_b32_e32 v55, 0xffff0000, v128
	v_exp_f32_e32 v52, v52
	v_exp_f32_e32 v53, v53
	v_exp_f32_e32 v58, v58
	v_exp_f32_e32 v59, v59
	v_pk_add_f32 v[44:45], v[44:45], 1.0 op_sel_hi:[1,0]
	v_rcp_f32_e32 v44, v44
	v_rcp_f32_e32 v45, v45
	v_pk_fma_f32 v[6:7], v[6:7], v[38:39], v[40:41]
	v_pk_mul_f32 v[46:47], v[6:7], v[42:43]
	v_pk_mul_f32 v[46:47], v[46:47], v[44:45]
	v_cvt_pk_bf16_f32 v48, v46, v47
	global_store_dword v[22:23], v48, off offset:3584
	s_waitcnt vmcnt(16)
	v_lshlrev_b32_e32 v24, 16, v130
	v_and_b32_e32 v25, 0xffff0000, v130
	v_lshlrev_b32_e32 v28, 16, v132
	v_and_b32_e32 v29, 0xffff0000, v132
	v_pk_mul_f32 v[24:25], v[24:25], s[56:57] op_sel_hi:[1,0]
	v_pk_mul_f32 v[30:31], v[28:29], s[58:59] op_sel_hi:[1,0]
	v_lshlrev_b32_e32 v26, 16, v131
	v_and_b32_e32 v27, 0xffff0000, v131
	v_exp_f32_e32 v24, v24
	v_exp_f32_e32 v25, v25
	v_exp_f32_e32 v30, v30
	v_exp_f32_e32 v31, v31
	v_pk_add_f32 v[58:59], v[58:59], 1.0 op_sel_hi:[1,0]
	v_rcp_f32_e32 v58, v58
	v_rcp_f32_e32 v59, v59
	v_pk_fma_f32 v[6:7], v[6:7], v[52:53], v[54:55]
	v_pk_mul_f32 v[60:61], v[6:7], v[56:57]
	v_pk_mul_f32 v[60:61], v[60:61], v[58:59]
	v_cvt_pk_bf16_f32 v62, v60, v61
	global_store_dword v[22:23], v62, off offset:3712
	s_waitcnt vmcnt(13)
	v_lshlrev_b32_e32 v38, 16, v133
	v_and_b32_e32 v39, 0xffff0000, v133
	v_lshlrev_b32_e32 v42, 16, v135
	v_and_b32_e32 v43, 0xffff0000, v135
	v_pk_mul_f32 v[38:39], v[38:39], s[56:57] op_sel_hi:[1,0]
	v_pk_mul_f32 v[44:45], v[42:43], s[58:59] op_sel_hi:[1,0]
	v_lshlrev_b32_e32 v40, 16, v134
	v_and_b32_e32 v41, 0xffff0000, v134
	v_exp_f32_e32 v38, v38
	v_exp_f32_e32 v39, v39
	v_exp_f32_e32 v44, v44
	v_exp_f32_e32 v45, v45
	v_pk_add_f32 v[30:31], v[30:31], 1.0 op_sel_hi:[1,0]
	v_rcp_f32_e32 v30, v30
	v_rcp_f32_e32 v31, v31
	v_pk_fma_f32 v[6:7], v[6:7], v[24:25], v[26:27]
	v_pk_mul_f32 v[32:33], v[6:7], v[28:29]
	v_pk_mul_f32 v[32:33], v[32:33], v[30:31]
	v_cvt_pk_bf16_f32 v34, v32, v33
	global_store_dword v[22:23], v34, off offset:3840
	v_pk_add_f32 v[44:45], v[44:45], 1.0 op_sel_hi:[1,0]
	v_rcp_f32_e32 v44, v44
	v_rcp_f32_e32 v45, v45
	v_pk_fma_f32 v[6:7], v[6:7], v[38:39], v[40:41]
	v_pk_mul_f32 v[46:47], v[6:7], v[42:43]
	v_pk_mul_f32 v[46:47], v[46:47], v[44:45]
	v_cvt_pk_bf16_f32 v48, v46, v47
	global_store_dword v[22:23], v48, off offset:3968
	s_add_i32 s3, s3, s74
	s_cmpk_gt_i32 s3, 0x7ff
	v_lshl_add_u64 v[0:1], v[0:1], 0, s[48:49]
	s_cbranch_scc0 .LBB0_547
	v_mov_b32_e32 v35, v16
